# noprio + OUT epilogue residual loads software-pipelined one row group ahead
# baseline (speedup 1.0000x reference)
; #define GAS __attribute__((address_space(1)))
;     __device__ __forceinline__ void operator()(const f32x4 (&acc)[2][2][4][2], const pg8::Unit& u, int wr, int wc, int fr, int fq) const {
;     ...
;         const bool odd = (fr & 1) != 0;
;         const unsigned eoA = (((unsigned)u.pm * 256u + hmo + (unsigned)(wr * 64 + (fr & ~1))) * D + u.pn * 256 + wc * 64) * 2u + (odd ? 64u : 0u) + 16u * fq;
; #pragma unroll
;         for (int ai = 0; ai < 2; ++ai)
; #pragma unroll
;             for (int m = 0; m < 4; ++m) { if (half && ai == 1) continue; const unsigned rr = (unsigned)(ai * 128 + m * 16); const unsigned o = eoA + rr * (D * 2u); float ss = 0.f;
;                 const u32x4 la = *(const GAS u32x4*)((const GAS char*)ws + (unsigned)WS_X16 + o), lb = *(const GAS u32x4*)((const GAS char*)ws + (unsigned)WS_X16 + o + D * 2u);
;                 u32x4 xr[2];
; #pragma unroll
;                 for (int c = 0; c < 4; ++c) { const unsigned pa = (unsigned)__builtin_amdgcn_update_dpp(0, (int)la[c], 0xB1, 0xF, 0xF, false), pb = (unsigned)__builtin_amdgcn_update_dpp(0, (int)lb[c], 0xB1, 0xF, 0xF, false);
;                     xr[0][c] = odd ? pb : la[c]; xr[1][c] = odd ? lb[c] : pa; }
;                 u32x4 w[2], v[2];
; #pragma unroll
;                 for (int bj = 0; bj < 2; ++bj) { const h16x8 xb = __builtin_bit_cast(h16x8, xr[bj]);
;                     const f32x4 x0 = (f32x4){(float)xb[0], (float)xb[1], (float)xb[2], (float)xb[3]} + g4[bj][0] * acc[ai][bj][m][0], x1 = (f32x4){(float)xb[4], (float)xb[5], (float)xb[6], (float)xb[7]} + g4[bj][1] * acc[ai][bj][m][1];
;                     ss += ((x0[0] * x0[0] + x0[1] * x0[1]) + (x0[2] * x0[2] + x0[3] * x0[3])) + ((x1[0] * x1[0] + x1[1] * x1[1]) + (x1[2] * x1[2] + x1[3] * x1[3]));
;                     w[bj].x = cvtpk_h(x0[0], x0[1]); w[bj].y = cvtpk_h(x0[2], x0[3]); w[bj].z = cvtpk_h(x1[0], x1[1]); w[bj].w = cvtpk_h(x1[2], x1[3]);
;                     const f32x4 y0 = x0 * a4[bj][0], y1 = x1 * a4[bj][1]; v[bj].x = cvtpk_h(y0[0], y0[1]); v[bj].y = cvtpk_h(y0[2], y0[3]); v[bj].z = cvtpk_h(y1[0], y1[1]); v[bj].w = cvtpk_h(y1[2], y1[3]); }
;                 stg_line_pair(ws, (unsigned)WS_X16 + o, D * 2u, w[0], w[1], odd);
;                 if (an_off) stg_line_pair(ws, (unsigned)WS_XS + o, D * 2u, v[0], v[1], odd);
;                 ss = red4(ss, fq * 16 + fr); if (fq == 0) stg_f1(ws, rqo + rr * 4u, ss);
.LBB0_463:
	s_lshl_b32 s19, s0, 8
	v_and_b32_e32 v172, 0x1ffffe, v191
	s_add_i32 s19, s19, s84
	v_add_u32_e32 v172, s19, v172
	v_lshl_add_u32 v172, v172, 10, s5
	v_and_b32_e32 v0, 1, v191
	v_or_b32_e32 v172, s29, v172
	v_cmp_eq_u32_e64 s[0:1], 0, v0
	v_lshlrev_b32_e32 v172, 1, v172
	v_lshlrev_b32_e32 v0, 6, v0
	v_lshlrev_b32_e32 v173, 4, v192
	s_add_u32 s42, s38, 0x16f80000
	v_add3_u32 v0, v0, v173, v172
	s_addc_u32 s43, s39, 0
	global_load_dwordx4 v[172:175], v0, s[42:43]
	global_load_dwordx4 v[176:179], v0, s[42:43] offset:2048
	v_mov_b32_e32 v193, v1
	v_mov_b32_e32 v194, v1
	s_and_b64 vcc, exec, s[2:3]
	s_waitcnt vmcnt(0)
	v_add_u32_e32 v222, 0x8000, v0
	global_load_dwordx4 v[214:217], v222, s[42:43]
	global_load_dwordx4 v[218:221], v222, s[42:43] offset:2048
	v_mov_b32_dpp v193, v172 quad_perm:[1,0,3,2] row_mask:0xf bank_mask:0xf
	v_mov_b32_dpp v194, v176 quad_perm:[1,0,3,2] row_mask:0xf bank_mask:0xf
	v_cndmask_b32_e64 v194, v194, v172, s[0:1]
	v_cndmask_b32_e64 v195, v176, v193, s[0:1]
	v_mov_b32_e32 v172, v1
	v_mov_b32_e32 v176, v1
	s_nop 0
	v_mov_b32_dpp v172, v173 quad_perm:[1,0,3,2] row_mask:0xf bank_mask:0xf
	v_mov_b32_dpp v176, v177 quad_perm:[1,0,3,2] row_mask:0xf bank_mask:0xf
	v_cndmask_b32_e64 v176, v176, v173, s[0:1]
	v_cndmask_b32_e64 v196, v177, v172, s[0:1]
	v_mov_b32_e32 v172, v1
	v_mov_b32_e32 v173, v1
	s_nop 0
	v_mov_b32_dpp v172, v174 quad_perm:[1,0,3,2] row_mask:0xf bank_mask:0xf
	v_mov_b32_dpp v173, v178 quad_perm:[1,0,3,2] row_mask:0xf bank_mask:0xf
	v_cndmask_b32_e64 v193, v173, v174, s[0:1]
	v_cndmask_b32_e64 v197, v178, v172, s[0:1]
	v_mov_b32_e32 v172, v1
	v_mov_b32_e32 v173, v1
	v_cvt_f32_f16_e32 v174, v176
	v_mov_b32_dpp v172, v175 quad_perm:[1,0,3,2] row_mask:0xf bank_mask:0xf
	v_mov_b32_dpp v173, v179 quad_perm:[1,0,3,2] row_mask:0xf bank_mask:0xf
	v_cndmask_b32_e64 v178, v173, v175, s[0:1]
	v_cndmask_b32_e64 v198, v179, v172, s[0:1]
	v_cvt_f32_f16_e32 v172, v194
	v_cvt_f32_f16_sdwa v173, v194 dst_sel:DWORD dst_unused:UNUSED_PAD src0_sel:WORD_1
	v_cvt_f32_f16_sdwa v175, v176 dst_sel:DWORD dst_unused:UNUSED_PAD src0_sel:WORD_1
	v_add_u32_e32 v194, 0x16f80000, v0
	v_pk_fma_f32 v[176:177], v[160:161], v[50:51], v[172:173]
	v_cvt_f32_f16_e32 v160, v193
	v_cvt_f32_f16_sdwa v161, v193 dst_sel:DWORD dst_unused:UNUSED_PAD src0_sel:WORD_1
	v_cvt_f32_f16_e32 v172, v178
	v_cvt_f32_f16_sdwa v173, v178 dst_sel:DWORD dst_unused:UNUSED_PAD src0_sel:WORD_1
	v_pk_fma_f32 v[162:163], v[162:163], v[52:53], v[174:175]
	v_cvt_pk_f16_f32 v199, v176, v177
	v_cvt_pk_f16_f32 v200, v162, v163
	v_pk_fma_f32 v[158:159], v[158:159], v[56:57], v[172:173]
	v_pk_fma_f32 v[172:173], v[156:157], v[54:55], v[160:161]
	v_cvt_f32_f16_e32 v156, v195
	v_cvt_f32_f16_sdwa v157, v195 dst_sel:DWORD dst_unused:UNUSED_PAD src0_sel:WORD_1
	v_cvt_f32_f16_e32 v160, v196
	v_cvt_f32_f16_sdwa v161, v196 dst_sel:DWORD dst_unused:UNUSED_PAD src0_sel:WORD_1
	v_cvt_pk_f16_f32 v201, v172, v173
	v_pk_fma_f32 v[178:179], v[152:153], v[58:59], v[156:157]
	v_cvt_f32_f16_e32 v152, v197
	v_cvt_f32_f16_sdwa v153, v197 dst_sel:DWORD dst_unused:UNUSED_PAD src0_sel:WORD_1
	v_pk_fma_f32 v[160:161], v[154:155], v[60:61], v[160:161]
	v_cvt_f32_f16_e32 v154, v198
	v_cvt_f32_f16_sdwa v155, v198 dst_sel:DWORD dst_unused:UNUSED_PAD src0_sel:WORD_1
	v_pk_fma_f32 v[174:175], v[148:149], v[62:63], v[152:153]
	v_mov_b32_e32 v153, v1
	v_cvt_pk_f16_f32 v148, v178, v179
	v_pk_fma_f32 v[156:157], v[150:151], v[64:65], v[154:155]
	v_mov_b32_e32 v152, v1
	v_mov_b32_dpp v153, v199 quad_perm:[1,0,3,2] row_mask:0xf bank_mask:0xf
	v_mov_b32_e32 v154, v1
	v_cvt_pk_f16_f32 v149, v160, v161
	v_mov_b32_dpp v152, v148 quad_perm:[1,0,3,2] row_mask:0xf bank_mask:0xf
	v_cndmask_b32_e64 v148, v148, v153, s[0:1]
	v_mov_b32_e32 v153, v1
	v_mov_b32_dpp v154, v200 quad_perm:[1,0,3,2] row_mask:0xf bank_mask:0xf
	v_mov_b32_e32 v155, v1
	v_cvt_pk_f16_f32 v150, v174, v175
	v_mov_b32_dpp v153, v149 quad_perm:[1,0,3,2] row_mask:0xf bank_mask:0xf
	v_cndmask_b32_e64 v149, v149, v154, s[0:1]
	v_mov_b32_e32 v154, v1
	v_mov_b32_dpp v155, v201 quad_perm:[1,0,3,2] row_mask:0xf bank_mask:0xf
	v_cvt_pk_f16_f32 v151, v156, v157
	v_mov_b32_dpp v154, v150 quad_perm:[1,0,3,2] row_mask:0xf bank_mask:0xf
	v_cndmask_b32_e64 v150, v150, v155, s[0:1]
	v_mov_b32_e32 v155, v1
	v_cvt_pk_f16_f32 v193, v158, v159
	v_mov_b32_e32 v195, v1
	v_mov_b32_dpp v155, v151 quad_perm:[1,0,3,2] row_mask:0xf bank_mask:0xf
	v_cndmask_b32_e64 v152, v152, v199, s[0:1]
	v_cndmask_b32_e64 v153, v153, v200, s[0:1]
	v_cndmask_b32_e64 v154, v154, v201, s[0:1]
	v_mov_b32_dpp v195, v193 quad_perm:[1,0,3,2] row_mask:0xf bank_mask:0xf
	v_cndmask_b32_e64 v155, v155, v193, s[0:1]
	v_cndmask_b32_e64 v151, v151, v195, s[0:1]
	global_store_dwordx4 v194, v[152:155], s[38:39]
	s_nop 1
	v_add_u32_e32 v152, 0x16f80800, v0
	global_store_dwordx4 v152, v[148:151], s[38:39]
	s_cbranch_vccnz .LBB0_465
	s_nop 0
	v_pk_mul_f32 v[148:149], v[32:33], v[156:157]
	v_pk_mul_f32 v[150:151], v[30:31], v[174:175]
	v_cvt_pk_f16_f32 v155, v148, v149
	v_cvt_pk_f16_f32 v154, v150, v151
	v_pk_mul_f32 v[148:149], v[28:29], v[160:161]
	v_pk_mul_f32 v[150:151], v[26:27], v[178:179]
	v_cvt_pk_f16_f32 v153, v148, v149
	v_cvt_pk_f16_f32 v152, v150, v151
	v_pk_mul_f32 v[148:149], v[24:25], v[158:159]
	v_pk_mul_f32 v[150:151], v[22:23], v[172:173]
	v_cvt_pk_f16_f32 v193, v148, v149
	v_cvt_pk_f16_f32 v194, v150, v151
	v_pk_mul_f32 v[148:149], v[20:21], v[162:163]
	v_pk_mul_f32 v[150:151], v[18:19], v[176:177]
	v_cvt_pk_f16_f32 v149, v148, v149
	v_cvt_pk_f16_f32 v148, v150, v151
	v_mov_b32_e32 v151, v1
	v_mov_b32_e32 v150, v1
	v_add_u32_e32 v195, 0x3d80000, v0
	v_mov_b32_dpp v151, v148 quad_perm:[1,0,3,2] row_mask:0xf bank_mask:0xf
	v_mov_b32_dpp v150, v152 quad_perm:[1,0,3,2] row_mask:0xf bank_mask:0xf
	v_cndmask_b32_e64 v152, v152, v151, s[0:1]
	v_mov_b32_e32 v151, v1
	v_cndmask_b32_e64 v148, v150, v148, s[0:1]
	v_mov_b32_e32 v150, v1
	v_mov_b32_dpp v151, v149 quad_perm:[1,0,3,2] row_mask:0xf bank_mask:0xf
	s_nop 0
	v_mov_b32_dpp v150, v153 quad_perm:[1,0,3,2] row_mask:0xf bank_mask:0xf
	v_cndmask_b32_e64 v153, v153, v151, s[0:1]
	v_mov_b32_e32 v151, v1
	v_cndmask_b32_e64 v149, v150, v149, s[0:1]
	v_mov_b32_e32 v150, v1
	v_mov_b32_dpp v151, v194 quad_perm:[1,0,3,2] row_mask:0xf bank_mask:0xf
	s_nop 0
	v_mov_b32_dpp v150, v154 quad_perm:[1,0,3,2] row_mask:0xf bank_mask:0xf
	v_cndmask_b32_e64 v154, v154, v151, s[0:1]
	v_mov_b32_e32 v151, v1
	v_cndmask_b32_e64 v150, v150, v194, s[0:1]
	v_mov_b32_e32 v194, v1
	v_mov_b32_dpp v151, v155 quad_perm:[1,0,3,2] row_mask:0xf bank_mask:0xf
	v_cndmask_b32_e64 v151, v151, v193, s[0:1]
	v_mov_b32_dpp v194, v193 quad_perm:[1,0,3,2] row_mask:0xf bank_mask:0xf
	v_cndmask_b32_e64 v155, v155, v194, s[0:1]
	global_store_dwordx4 v195, v[148:151], s[38:39]
	s_nop 1
	v_add_u32_e32 v148, 0x3d80800, v0
	global_store_dwordx4 v148, v[152:155], s[38:39]

; #define GAS __attribute__((address_space(1)))
;     __device__ __forceinline__ void operator()(const f32x4 (&acc)[2][2][4][2], const pg8::Unit& u, int wr, int wc, int fr, int fq) const {
;     ...
;             for (int m = 0; m < 4; ++m) { if (half && ai == 1) continue; const unsigned rr = (unsigned)(ai * 128 + m * 16); const unsigned o = eoA + rr * (D * 2u); float ss = 0.f;
;                 const u32x4 la = *(const GAS u32x4*)((const GAS char*)ws + (unsigned)WS_X16 + o), lb = *(const GAS u32x4*)((const GAS char*)ws + (unsigned)WS_X16 + o + D * 2u);
.LBB0_467:
	s_or_b64 exec, exec, s[44:45]
	s_and_b64 vcc, exec, s[2:3]
	s_cbranch_vccnz .Lo_w3_1
	s_waitcnt vmcnt(5)
	s_branch .Lo_wd_1

; #define GAS __attribute__((address_space(1)))
; __device__ __forceinline__ unsigned cvtpk_h(float lo, float hi) { f32x2 v = {lo, hi}; h16x2 b = __builtin_convertvector(v, h16x2); return __builtin_bit_cast(unsigned, b); }
;     __device__ __forceinline__ void operator()(const f32x4 (&acc)[2][2][4][2], const pg8::Unit& u, int wr, int wc, int fr, int fq) const {
;     ...
;             for (int m = 0; m < 4; ++m) { if (half && ai == 1) continue; const unsigned rr = (unsigned)(ai * 128 + m * 16); const unsigned o = eoA + rr * (D * 2u); float ss = 0.f;
;                 const u32x4 la = *(const GAS u32x4*)((const GAS char*)ws + (unsigned)WS_X16 + o), lb = *(const GAS u32x4*)((const GAS char*)ws + (unsigned)WS_X16 + o + D * 2u);
;                 u32x4 xr[2];
; #pragma unroll
;                 for (int c = 0; c < 4; ++c) { const unsigned pa = (unsigned)__builtin_amdgcn_update_dpp(0, (int)la[c], 0xB1, 0xF, 0xF, false), pb = (unsigned)__builtin_amdgcn_update_dpp(0, (int)lb[c], 0xB1, 0xF, 0xF, false);
;                     xr[0][c] = odd ? pb : la[c]; xr[1][c] = odd ? lb[c] : pa; }
;                 u32x4 w[2], v[2];
; #pragma unroll
;                 for (int bj = 0; bj < 2; ++bj) { const h16x8 xb = __builtin_bit_cast(h16x8, xr[bj]);
;                     const f32x4 x0 = (f32x4){(float)xb[0], (float)xb[1], (float)xb[2], (float)xb[3]} + g4[bj][0] * acc[ai][bj][m][0], x1 = (f32x4){(float)xb[4], (float)xb[5], (float)xb[6], (float)xb[7]} + g4[bj][1] * acc[ai][bj][m][1];
;                     ss += ((x0[0] * x0[0] + x0[1] * x0[1]) + (x0[2] * x0[2] + x0[3] * x0[3])) + ((x1[0] * x1[0] + x1[1] * x1[1]) + (x1[2] * x1[2] + x1[3] * x1[3]));
;                     w[bj].x = cvtpk_h(x0[0], x0[1]); w[bj].y = cvtpk_h(x0[2], x0[3]); w[bj].z = cvtpk_h(x1[0], x1[1]); w[bj].w = cvtpk_h(x1[2], x1[3]);
;                     const f32x4 y0 = x0 * a4[bj][0], y1 = x1 * a4[bj][1]; v[bj].x = cvtpk_h(y0[0], y0[1]); v[bj].y = cvtpk_h(y0[2], y0[3]); v[bj].z = cvtpk_h(y1[0], y1[1]); v[bj].w = cvtpk_h(y1[2], y1[3]); }
;                 stg_line_pair(ws, (unsigned)WS_X16 + o, D * 2u, w[0], w[1], odd);
;                 if (an_off) stg_line_pair(ws, (unsigned)WS_XS + o, D * 2u, v[0], v[1], odd);
.Lo_wd_1:
	v_mov_b32_e32 v150, v214
	v_mov_b32_e32 v151, v215
	v_mov_b32_e32 v152, v216
	v_mov_b32_e32 v153, v217
	v_mov_b32_e32 v154, v218
	v_mov_b32_e32 v155, v219
	v_mov_b32_e32 v156, v220
	v_mov_b32_e32 v157, v221
	v_add_u32_e32 v222, 0x10000, v0
	global_load_dwordx4 v[214:217], v222, s[42:43]
	global_load_dwordx4 v[218:221], v222, s[42:43] offset:2048
	v_mov_b32_e32 v149, v1
	v_mov_b32_e32 v158, v1
	v_add_u32_e32 v161, 0x16f88000, v0
	s_and_b64 vcc, exec, s[2:3]
	v_mov_b32_dpp v149, v150 quad_perm:[1,0,3,2] row_mask:0xf bank_mask:0xf
	v_mov_b32_dpp v158, v154 quad_perm:[1,0,3,2] row_mask:0xf bank_mask:0xf
	v_cndmask_b32_e64 v158, v158, v150, s[0:1]
	v_cndmask_b32_e64 v149, v154, v149, s[0:1]
	v_mov_b32_e32 v150, v1
	v_mov_b32_e32 v154, v1
	s_nop 0
	v_mov_b32_dpp v150, v151 quad_perm:[1,0,3,2] row_mask:0xf bank_mask:0xf
	v_mov_b32_dpp v154, v155 quad_perm:[1,0,3,2] row_mask:0xf bank_mask:0xf
	v_cndmask_b32_e64 v154, v154, v151, s[0:1]
	v_cndmask_b32_e64 v155, v155, v150, s[0:1]
	v_mov_b32_e32 v150, v1
	v_mov_b32_e32 v151, v1
	s_nop 0
	v_mov_b32_dpp v150, v152 quad_perm:[1,0,3,2] row_mask:0xf bank_mask:0xf
	v_mov_b32_dpp v151, v156 quad_perm:[1,0,3,2] row_mask:0xf bank_mask:0xf
	v_cndmask_b32_e64 v159, v151, v152, s[0:1]
	v_cndmask_b32_e64 v156, v156, v150, s[0:1]
	v_mov_b32_e32 v150, v1
	v_mov_b32_e32 v151, v1
	v_cvt_f32_f16_e32 v152, v154
	v_mov_b32_dpp v150, v153 quad_perm:[1,0,3,2] row_mask:0xf bank_mask:0xf
	v_mov_b32_dpp v151, v157 quad_perm:[1,0,3,2] row_mask:0xf bank_mask:0xf
	v_cndmask_b32_e64 v160, v151, v153, s[0:1]
	v_cndmask_b32_e64 v157, v157, v150, s[0:1]
	v_cvt_f32_f16_e32 v150, v158
	v_cvt_f32_f16_sdwa v151, v158 dst_sel:DWORD dst_unused:UNUSED_PAD src0_sel:WORD_1
	v_cvt_f32_f16_sdwa v153, v154 dst_sel:DWORD dst_unused:UNUSED_PAD src0_sel:WORD_1
	v_pk_fma_f32 v[144:145], v[144:145], v[50:51], v[150:151]
	v_cvt_f32_f16_e32 v150, v159
	v_cvt_f32_f16_sdwa v151, v159 dst_sel:DWORD dst_unused:UNUSED_PAD src0_sel:WORD_1
	v_pk_fma_f32 v[146:147], v[146:147], v[52:53], v[152:153]
	v_cvt_f32_f16_e32 v152, v160
	v_cvt_f32_f16_sdwa v153, v160 dst_sel:DWORD dst_unused:UNUSED_PAD src0_sel:WORD_1
	v_pk_fma_f32 v[140:141], v[140:141], v[54:55], v[150:151]
	v_cvt_f32_f16_e32 v150, v149
	v_cvt_f32_f16_sdwa v151, v149 dst_sel:DWORD dst_unused:UNUSED_PAD src0_sel:WORD_1
	v_pk_fma_f32 v[142:143], v[142:143], v[56:57], v[152:153]
	v_cvt_f32_f16_e32 v152, v155
	v_cvt_f32_f16_sdwa v153, v155 dst_sel:DWORD dst_unused:UNUSED_PAD src0_sel:WORD_1
	v_pk_fma_f32 v[136:137], v[136:137], v[58:59], v[150:151]
	v_cvt_f32_f16_e32 v150, v156
	v_cvt_f32_f16_sdwa v151, v156 dst_sel:DWORD dst_unused:UNUSED_PAD src0_sel:WORD_1
	v_pk_fma_f32 v[138:139], v[138:139], v[60:61], v[152:153]
	v_cvt_f32_f16_e32 v152, v157
	v_cvt_f32_f16_sdwa v153, v157 dst_sel:DWORD dst_unused:UNUSED_PAD src0_sel:WORD_1
	v_cvt_pk_f16_f32 v154, v144, v145
	v_pk_fma_f32 v[132:133], v[132:133], v[62:63], v[150:151]
	v_cvt_pk_f16_f32 v149, v136, v137
	v_mov_b32_e32 v150, v1
	v_mov_b32_e32 v151, v1
	v_pk_fma_f32 v[134:135], v[134:135], v[64:65], v[152:153]
	v_mov_b32_dpp v150, v149 quad_perm:[1,0,3,2] row_mask:0xf bank_mask:0xf
	v_mov_b32_dpp v151, v154 quad_perm:[1,0,3,2] row_mask:0xf bank_mask:0xf
	v_cvt_pk_f16_f32 v152, v138, v139
	v_cndmask_b32_e64 v150, v150, v154, s[0:1]
	v_cndmask_b32_e64 v154, v149, v151, s[0:1]
	v_mov_b32_e32 v149, v1
	v_cvt_pk_f16_f32 v158, v146, v147
	v_cvt_pk_f16_f32 v153, v132, v133
	v_mov_b32_dpp v149, v152 quad_perm:[1,0,3,2] row_mask:0xf bank_mask:0xf
	v_mov_b32_e32 v155, v1
	v_cndmask_b32_e64 v151, v149, v158, s[0:1]
	v_mov_b32_e32 v149, v1
	v_cvt_pk_f16_f32 v159, v140, v141
	v_mov_b32_dpp v155, v158 quad_perm:[1,0,3,2] row_mask:0xf bank_mask:0xf
	v_mov_b32_dpp v149, v153 quad_perm:[1,0,3,2] row_mask:0xf bank_mask:0xf
	v_cvt_pk_f16_f32 v160, v142, v143
	v_cvt_pk_f16_f32 v157, v134, v135
	v_cndmask_b32_e64 v155, v152, v155, s[0:1]
	v_mov_b32_e32 v156, v1
	v_cndmask_b32_e64 v152, v149, v159, s[0:1]
	v_mov_b32_e32 v149, v1
	v_mov_b32_e32 v158, v1
	v_mov_b32_dpp v156, v159 quad_perm:[1,0,3,2] row_mask:0xf bank_mask:0xf
	v_mov_b32_dpp v149, v157 quad_perm:[1,0,3,2] row_mask:0xf bank_mask:0xf
	v_mov_b32_dpp v158, v160 quad_perm:[1,0,3,2] row_mask:0xf bank_mask:0xf
	v_cndmask_b32_e64 v156, v153, v156, s[0:1]
	v_cndmask_b32_e64 v153, v149, v160, s[0:1]
	v_cndmask_b32_e64 v157, v157, v158, s[0:1]
	v_add_u32_e32 v149, 0x16f88800, v0
	global_store_dwordx4 v161, v[150:153], s[38:39]
	global_store_dwordx4 v149, v[154:157], s[38:39]
	s_cbranch_vccnz .LBB0_469
	v_pk_mul_f32 v[150:151], v[32:33], v[134:135]
	v_pk_mul_f32 v[152:153], v[30:31], v[132:133]
	v_cvt_pk_f16_f32 v149, v150, v151
	v_cvt_pk_f16_f32 v156, v152, v153
	v_pk_mul_f32 v[150:151], v[28:29], v[138:139]
	v_pk_mul_f32 v[152:153], v[26:27], v[136:137]
	v_cvt_pk_f16_f32 v155, v150, v151
	v_cvt_pk_f16_f32 v154, v152, v153
	v_pk_mul_f32 v[150:151], v[24:25], v[142:143]
	v_pk_mul_f32 v[152:153], v[22:23], v[140:141]
	v_cvt_pk_f16_f32 v157, v150, v151
	v_cvt_pk_f16_f32 v158, v152, v153
	v_pk_mul_f32 v[150:151], v[20:21], v[146:147]
	v_pk_mul_f32 v[152:153], v[18:19], v[144:145]
	v_cvt_pk_f16_f32 v151, v150, v151
	v_cvt_pk_f16_f32 v150, v152, v153
	v_mov_b32_e32 v152, v1
	v_mov_b32_e32 v153, v1
	v_add_u32_e32 v159, 0x3d88000, v0
	v_mov_b32_dpp v152, v154 quad_perm:[1,0,3,2] row_mask:0xf bank_mask:0xf
	v_mov_b32_dpp v153, v150 quad_perm:[1,0,3,2] row_mask:0xf bank_mask:0xf
	v_cndmask_b32_e64 v150, v152, v150, s[0:1]
	v_cndmask_b32_e64 v154, v154, v153, s[0:1]
	v_mov_b32_e32 v152, v1
	v_mov_b32_e32 v153, v1
	s_nop 0
	v_mov_b32_dpp v152, v155 quad_perm:[1,0,3,2] row_mask:0xf bank_mask:0xf
	v_mov_b32_dpp v153, v151 quad_perm:[1,0,3,2] row_mask:0xf bank_mask:0xf
	v_cndmask_b32_e64 v151, v152, v151, s[0:1]
	v_cndmask_b32_e64 v155, v155, v153, s[0:1]
	v_mov_b32_e32 v152, v1
	v_mov_b32_e32 v153, v1
	s_nop 0
	v_mov_b32_dpp v152, v156 quad_perm:[1,0,3,2] row_mask:0xf bank_mask:0xf
	v_mov_b32_dpp v153, v158 quad_perm:[1,0,3,2] row_mask:0xf bank_mask:0xf
	v_cndmask_b32_e64 v152, v152, v158, s[0:1]
	v_cndmask_b32_e64 v156, v156, v153, s[0:1]
	v_mov_b32_e32 v153, v1
	v_mov_b32_e32 v158, v1
	s_nop 0
	v_mov_b32_dpp v153, v149 quad_perm:[1,0,3,2] row_mask:0xf bank_mask:0xf
	v_mov_b32_dpp v158, v157 quad_perm:[1,0,3,2] row_mask:0xf bank_mask:0xf
	v_cndmask_b32_e64 v153, v153, v157, s[0:1]
	v_cndmask_b32_e64 v157, v149, v158, s[0:1]
	v_add_u32_e32 v149, 0x3d88800, v0
	global_store_dwordx4 v159, v[150:153], s[38:39]
	global_store_dwordx4 v149, v[154:157], s[38:39]

; #define GAS __attribute__((address_space(1)))
; __device__ __forceinline__ unsigned cvtpk_h(float lo, float hi) { f32x2 v = {lo, hi}; h16x2 b = __builtin_convertvector(v, h16x2); return __builtin_bit_cast(unsigned, b); }
;     __device__ __forceinline__ void operator()(const f32x4 (&acc)[2][2][4][2], const pg8::Unit& u, int wr, int wc, int fr, int fq) const {
;     ...
;             for (int m = 0; m < 4; ++m) { if (half && ai == 1) continue; const unsigned rr = (unsigned)(ai * 128 + m * 16); const unsigned o = eoA + rr * (D * 2u); float ss = 0.f;
;                 const u32x4 la = *(const GAS u32x4*)((const GAS char*)ws + (unsigned)WS_X16 + o), lb = *(const GAS u32x4*)((const GAS char*)ws + (unsigned)WS_X16 + o + D * 2u);
;                 u32x4 xr[2];
; #pragma unroll
;                 for (int c = 0; c < 4; ++c) { const unsigned pa = (unsigned)__builtin_amdgcn_update_dpp(0, (int)la[c], 0xB1, 0xF, 0xF, false), pb = (unsigned)__builtin_amdgcn_update_dpp(0, (int)lb[c], 0xB1, 0xF, 0xF, false);
;                     xr[0][c] = odd ? pb : la[c]; xr[1][c] = odd ? lb[c] : pa; }
;                 u32x4 w[2], v[2];
; #pragma unroll
;                 for (int bj = 0; bj < 2; ++bj) { const h16x8 xb = __builtin_bit_cast(h16x8, xr[bj]);
;                     const f32x4 x0 = (f32x4){(float)xb[0], (float)xb[1], (float)xb[2], (float)xb[3]} + g4[bj][0] * acc[ai][bj][m][0], x1 = (f32x4){(float)xb[4], (float)xb[5], (float)xb[6], (float)xb[7]} + g4[bj][1] * acc[ai][bj][m][1];
;                     ss += ((x0[0] * x0[0] + x0[1] * x0[1]) + (x0[2] * x0[2] + x0[3] * x0[3])) + ((x1[0] * x1[0] + x1[1] * x1[1]) + (x1[2] * x1[2] + x1[3] * x1[3]));
;                     w[bj].x = cvtpk_h(x0[0], x0[1]); w[bj].y = cvtpk_h(x0[2], x0[3]); w[bj].z = cvtpk_h(x1[0], x1[1]); w[bj].w = cvtpk_h(x1[2], x1[3]);
;                     const f32x4 y0 = x0 * a4[bj][0], y1 = x1 * a4[bj][1]; v[bj].x = cvtpk_h(y0[0], y0[1]); v[bj].y = cvtpk_h(y0[2], y0[3]); v[bj].z = cvtpk_h(y1[0], y1[1]); v[bj].w = cvtpk_h(y1[2], y1[3]); }
;                 stg_line_pair(ws, (unsigned)WS_X16 + o, D * 2u, w[0], w[1], odd);
;                 if (an_off) stg_line_pair(ws, (unsigned)WS_XS + o, D * 2u, v[0], v[1], odd);
.Lo_wd_2:
	v_mov_b32_e32 v132, v214
	v_mov_b32_e32 v133, v215
	v_mov_b32_e32 v134, v216
	v_mov_b32_e32 v135, v217
	v_mov_b32_e32 v136, v218
	v_mov_b32_e32 v137, v219
	v_mov_b32_e32 v138, v220
	v_mov_b32_e32 v139, v221
	v_add_u32_e32 v222, 0x18000, v0
	global_load_dwordx4 v[214:217], v222, s[42:43]
	global_load_dwordx4 v[218:221], v222, s[42:43] offset:2048
	v_mov_b32_e32 v140, v1
	v_mov_b32_e32 v141, v1
	v_add_u32_e32 v144, 0x16f90000, v0
	s_and_b64 vcc, exec, s[2:3]
	v_mov_b32_dpp v140, v132 quad_perm:[1,0,3,2] row_mask:0xf bank_mask:0xf
	v_mov_b32_dpp v141, v136 quad_perm:[1,0,3,2] row_mask:0xf bank_mask:0xf
	v_cndmask_b32_e64 v141, v141, v132, s[0:1]
	v_cndmask_b32_e64 v136, v136, v140, s[0:1]
	v_mov_b32_e32 v132, v1
	v_mov_b32_e32 v140, v1
	s_nop 0
	v_mov_b32_dpp v132, v133 quad_perm:[1,0,3,2] row_mask:0xf bank_mask:0xf
	v_mov_b32_dpp v140, v137 quad_perm:[1,0,3,2] row_mask:0xf bank_mask:0xf
	v_cndmask_b32_e64 v140, v140, v133, s[0:1]
	v_cndmask_b32_e64 v137, v137, v132, s[0:1]
	v_mov_b32_e32 v132, v1
	v_mov_b32_e32 v133, v1
	s_nop 0
	v_mov_b32_dpp v132, v134 quad_perm:[1,0,3,2] row_mask:0xf bank_mask:0xf
	v_mov_b32_dpp v133, v138 quad_perm:[1,0,3,2] row_mask:0xf bank_mask:0xf
	v_cndmask_b32_e64 v142, v133, v134, s[0:1]
	v_cndmask_b32_e64 v138, v138, v132, s[0:1]
	v_mov_b32_e32 v132, v1
	v_mov_b32_e32 v133, v1
	v_cvt_f32_f16_e32 v134, v140
	v_mov_b32_dpp v132, v135 quad_perm:[1,0,3,2] row_mask:0xf bank_mask:0xf
	v_mov_b32_dpp v133, v139 quad_perm:[1,0,3,2] row_mask:0xf bank_mask:0xf
	v_cndmask_b32_e64 v143, v133, v135, s[0:1]
	v_cndmask_b32_e64 v139, v139, v132, s[0:1]
	v_cvt_f32_f16_e32 v132, v141
	v_cvt_f32_f16_sdwa v133, v141 dst_sel:DWORD dst_unused:UNUSED_PAD src0_sel:WORD_1
	v_cvt_f32_f16_sdwa v135, v140 dst_sel:DWORD dst_unused:UNUSED_PAD src0_sel:WORD_1
	v_pk_fma_f32 v[126:127], v[126:127], v[50:51], v[132:133]
	v_cvt_f32_f16_e32 v132, v142
	v_cvt_f32_f16_sdwa v133, v142 dst_sel:DWORD dst_unused:UNUSED_PAD src0_sel:WORD_1
	v_pk_fma_f32 v[128:129], v[128:129], v[52:53], v[134:135]
	v_cvt_f32_f16_e32 v134, v143
	v_cvt_f32_f16_sdwa v135, v143 dst_sel:DWORD dst_unused:UNUSED_PAD src0_sel:WORD_1
	v_pk_fma_f32 v[122:123], v[122:123], v[54:55], v[132:133]
	v_cvt_f32_f16_e32 v132, v136
	v_cvt_f32_f16_sdwa v133, v136 dst_sel:DWORD dst_unused:UNUSED_PAD src0_sel:WORD_1
	v_pk_fma_f32 v[124:125], v[124:125], v[56:57], v[134:135]
	v_cvt_f32_f16_e32 v134, v137
	v_cvt_f32_f16_sdwa v135, v137 dst_sel:DWORD dst_unused:UNUSED_PAD src0_sel:WORD_1
	v_pk_fma_f32 v[118:119], v[118:119], v[58:59], v[132:133]
	v_cvt_f32_f16_e32 v132, v138
	v_cvt_f32_f16_sdwa v133, v138 dst_sel:DWORD dst_unused:UNUSED_PAD src0_sel:WORD_1
	v_pk_fma_f32 v[120:121], v[120:121], v[60:61], v[134:135]
	v_cvt_f32_f16_e32 v134, v139
	v_cvt_f32_f16_sdwa v135, v139 dst_sel:DWORD dst_unused:UNUSED_PAD src0_sel:WORD_1
	v_cvt_pk_f16_f32 v140, v126, v127
	v_mov_b32_e32 v136, v1
	v_cvt_pk_f16_f32 v141, v128, v129
	v_pk_fma_f32 v[114:115], v[114:115], v[62:63], v[132:133]
	v_cvt_pk_f16_f32 v133, v118, v119
	v_mov_b32_e32 v132, v1
	v_mov_b32_dpp v136, v140 quad_perm:[1,0,3,2] row_mask:0xf bank_mask:0xf
	v_mov_b32_e32 v137, v1
	v_cvt_pk_f16_f32 v142, v122, v123
	v_pk_fma_f32 v[116:117], v[116:117], v[64:65], v[134:135]
	v_cvt_pk_f16_f32 v134, v120, v121
	v_mov_b32_dpp v132, v133 quad_perm:[1,0,3,2] row_mask:0xf bank_mask:0xf
	v_cndmask_b32_e64 v136, v133, v136, s[0:1]
	v_mov_b32_e32 v133, v1
	v_mov_b32_dpp v137, v141 quad_perm:[1,0,3,2] row_mask:0xf bank_mask:0xf
	v_mov_b32_e32 v138, v1
	v_cvt_pk_f16_f32 v135, v114, v115
	v_mov_b32_dpp v133, v134 quad_perm:[1,0,3,2] row_mask:0xf bank_mask:0xf
	v_cndmask_b32_e64 v137, v134, v137, s[0:1]
	v_mov_b32_e32 v134, v1
	v_mov_b32_dpp v138, v142 quad_perm:[1,0,3,2] row_mask:0xf bank_mask:0xf
	v_cvt_pk_f16_f32 v139, v116, v117
	v_mov_b32_dpp v134, v135 quad_perm:[1,0,3,2] row_mask:0xf bank_mask:0xf
	v_cndmask_b32_e64 v138, v135, v138, s[0:1]
	v_mov_b32_e32 v135, v1
	v_cvt_pk_f16_f32 v143, v124, v125
	v_cndmask_b32_e64 v132, v132, v140, s[0:1]
	v_mov_b32_dpp v135, v139 quad_perm:[1,0,3,2] row_mask:0xf bank_mask:0xf
	v_mov_b32_e32 v140, v1
	v_cndmask_b32_e64 v133, v133, v141, s[0:1]
	v_cndmask_b32_e64 v134, v134, v142, s[0:1]
	v_mov_b32_dpp v140, v143 quad_perm:[1,0,3,2] row_mask:0xf bank_mask:0xf
	v_cndmask_b32_e64 v135, v135, v143, s[0:1]
	v_cndmask_b32_e64 v139, v139, v140, s[0:1]
	global_store_dwordx4 v144, v[132:135], s[38:39]
	s_nop 1
	v_add_u32_e32 v132, 0x16f90800, v0
	global_store_dwordx4 v132, v[136:139], s[38:39]
	s_cbranch_vccnz .LBB0_473
	v_pk_mul_f32 v[132:133], v[32:33], v[116:117]
	v_pk_mul_f32 v[134:135], v[30:31], v[114:115]
	v_cvt_pk_f16_f32 v139, v132, v133
	v_cvt_pk_f16_f32 v138, v134, v135
	v_pk_mul_f32 v[132:133], v[28:29], v[120:121]
	v_pk_mul_f32 v[134:135], v[26:27], v[118:119]
	v_cvt_pk_f16_f32 v137, v132, v133
	v_cvt_pk_f16_f32 v136, v134, v135
	v_pk_mul_f32 v[132:133], v[24:25], v[124:125]
	v_pk_mul_f32 v[134:135], v[22:23], v[122:123]
	v_cvt_pk_f16_f32 v140, v132, v133
	v_cvt_pk_f16_f32 v141, v134, v135
	v_pk_mul_f32 v[132:133], v[20:21], v[128:129]
	v_pk_mul_f32 v[134:135], v[18:19], v[126:127]
	v_cvt_pk_f16_f32 v133, v132, v133
	v_cvt_pk_f16_f32 v132, v134, v135
	v_mov_b32_e32 v135, v1
	v_mov_b32_e32 v134, v1
	v_add_u32_e32 v142, 0x3d90000, v0
	v_mov_b32_dpp v135, v132 quad_perm:[1,0,3,2] row_mask:0xf bank_mask:0xf
	v_mov_b32_dpp v134, v136 quad_perm:[1,0,3,2] row_mask:0xf bank_mask:0xf
	v_cndmask_b32_e64 v136, v136, v135, s[0:1]
	v_mov_b32_e32 v135, v1
	v_cndmask_b32_e64 v132, v134, v132, s[0:1]
	v_mov_b32_e32 v134, v1
	v_mov_b32_dpp v135, v133 quad_perm:[1,0,3,2] row_mask:0xf bank_mask:0xf
	s_nop 0
	v_mov_b32_dpp v134, v137 quad_perm:[1,0,3,2] row_mask:0xf bank_mask:0xf
	v_cndmask_b32_e64 v137, v137, v135, s[0:1]
	v_mov_b32_e32 v135, v1
	v_cndmask_b32_e64 v133, v134, v133, s[0:1]
	v_mov_b32_e32 v134, v1
	v_mov_b32_dpp v135, v141 quad_perm:[1,0,3,2] row_mask:0xf bank_mask:0xf
	s_nop 0
	v_mov_b32_dpp v134, v138 quad_perm:[1,0,3,2] row_mask:0xf bank_mask:0xf
	v_cndmask_b32_e64 v138, v138, v135, s[0:1]
	v_mov_b32_e32 v135, v1
	v_cndmask_b32_e64 v134, v134, v141, s[0:1]
	v_mov_b32_e32 v141, v1
	v_mov_b32_dpp v135, v139 quad_perm:[1,0,3,2] row_mask:0xf bank_mask:0xf
	v_cndmask_b32_e64 v135, v135, v140, s[0:1]
	v_mov_b32_dpp v141, v140 quad_perm:[1,0,3,2] row_mask:0xf bank_mask:0xf
	v_cndmask_b32_e64 v139, v139, v141, s[0:1]
	global_store_dwordx4 v142, v[132:135], s[38:39]
	s_nop 1
	v_add_u32_e32 v132, 0x3d90800, v0
	global_store_dwordx4 v132, v[136:139], s[38:39]

; #define GAS __attribute__((address_space(1)))
; __device__ __forceinline__ unsigned cvtpk_h(float lo, float hi) { f32x2 v = {lo, hi}; h16x2 b = __builtin_convertvector(v, h16x2); return __builtin_bit_cast(unsigned, b); }
;     __device__ __forceinline__ void operator()(const f32x4 (&acc)[2][2][4][2], const pg8::Unit& u, int wr, int wc, int fr, int fq) const {
;     ...
;             for (int m = 0; m < 4; ++m) { if (half && ai == 1) continue; const unsigned rr = (unsigned)(ai * 128 + m * 16); const unsigned o = eoA + rr * (D * 2u); float ss = 0.f;
;                 const u32x4 la = *(const GAS u32x4*)((const GAS char*)ws + (unsigned)WS_X16 + o), lb = *(const GAS u32x4*)((const GAS char*)ws + (unsigned)WS_X16 + o + D * 2u);
;                 u32x4 xr[2];
; #pragma unroll
;                 for (int c = 0; c < 4; ++c) { const unsigned pa = (unsigned)__builtin_amdgcn_update_dpp(0, (int)la[c], 0xB1, 0xF, 0xF, false), pb = (unsigned)__builtin_amdgcn_update_dpp(0, (int)lb[c], 0xB1, 0xF, 0xF, false);
;                     xr[0][c] = odd ? pb : la[c]; xr[1][c] = odd ? lb[c] : pa; }
;                 u32x4 w[2], v[2];
; #pragma unroll
;                 for (int bj = 0; bj < 2; ++bj) { const h16x8 xb = __builtin_bit_cast(h16x8, xr[bj]);
;                     const f32x4 x0 = (f32x4){(float)xb[0], (float)xb[1], (float)xb[2], (float)xb[3]} + g4[bj][0] * acc[ai][bj][m][0], x1 = (f32x4){(float)xb[4], (float)xb[5], (float)xb[6], (float)xb[7]} + g4[bj][1] * acc[ai][bj][m][1];
;                     ss += ((x0[0] * x0[0] + x0[1] * x0[1]) + (x0[2] * x0[2] + x0[3] * x0[3])) + ((x1[0] * x1[0] + x1[1] * x1[1]) + (x1[2] * x1[2] + x1[3] * x1[3]));
;                     w[bj].x = cvtpk_h(x0[0], x0[1]); w[bj].y = cvtpk_h(x0[2], x0[3]); w[bj].z = cvtpk_h(x1[0], x1[1]); w[bj].w = cvtpk_h(x1[2], x1[3]);
;                     const f32x4 y0 = x0 * a4[bj][0], y1 = x1 * a4[bj][1]; v[bj].x = cvtpk_h(y0[0], y0[1]); v[bj].y = cvtpk_h(y0[2], y0[3]); v[bj].z = cvtpk_h(y1[0], y1[1]); v[bj].w = cvtpk_h(y1[2], y1[3]); }
;                 stg_line_pair(ws, (unsigned)WS_X16 + o, D * 2u, w[0], w[1], odd);
;                 if (an_off) stg_line_pair(ws, (unsigned)WS_XS + o, D * 2u, v[0], v[1], odd);
.Lo_wd_3:
	v_mov_b32_e32 v114, v214
	v_mov_b32_e32 v115, v215
	v_mov_b32_e32 v116, v216
	v_mov_b32_e32 v117, v217
	v_mov_b32_e32 v118, v218
	v_mov_b32_e32 v119, v219
	v_mov_b32_e32 v120, v220
	v_mov_b32_e32 v121, v221
	v_add_u32_e32 v222, 0x40000, v0
	global_load_dwordx4 v[214:217], v222, s[42:43]
	global_load_dwordx4 v[218:221], v222, s[42:43] offset:2048
	v_mov_b32_e32 v122, v1
	v_mov_b32_e32 v123, v1
	v_add_u32_e32 v126, 0x16f98000, v0
	s_and_b64 vcc, exec, s[2:3]
	v_mov_b32_dpp v122, v114 quad_perm:[1,0,3,2] row_mask:0xf bank_mask:0xf
	v_mov_b32_dpp v123, v118 quad_perm:[1,0,3,2] row_mask:0xf bank_mask:0xf
	v_cndmask_b32_e64 v123, v123, v114, s[0:1]
	v_cndmask_b32_e64 v118, v118, v122, s[0:1]
	v_mov_b32_e32 v114, v1
	v_mov_b32_e32 v122, v1
	s_nop 0
	v_mov_b32_dpp v114, v115 quad_perm:[1,0,3,2] row_mask:0xf bank_mask:0xf
	v_mov_b32_dpp v122, v119 quad_perm:[1,0,3,2] row_mask:0xf bank_mask:0xf
	v_cndmask_b32_e64 v122, v122, v115, s[0:1]
	v_cndmask_b32_e64 v119, v119, v114, s[0:1]
	v_mov_b32_e32 v114, v1
	v_mov_b32_e32 v115, v1
	s_nop 0
	v_mov_b32_dpp v114, v116 quad_perm:[1,0,3,2] row_mask:0xf bank_mask:0xf
	v_mov_b32_dpp v115, v120 quad_perm:[1,0,3,2] row_mask:0xf bank_mask:0xf
	v_cndmask_b32_e64 v124, v115, v116, s[0:1]
	v_cndmask_b32_e64 v120, v120, v114, s[0:1]
	v_mov_b32_e32 v114, v1
	v_mov_b32_e32 v115, v1
	v_cvt_f32_f16_e32 v116, v122
	v_mov_b32_dpp v114, v117 quad_perm:[1,0,3,2] row_mask:0xf bank_mask:0xf
	v_mov_b32_dpp v115, v121 quad_perm:[1,0,3,2] row_mask:0xf bank_mask:0xf
	v_cndmask_b32_e64 v125, v115, v117, s[0:1]
	v_cndmask_b32_e64 v121, v121, v114, s[0:1]
	v_cvt_f32_f16_e32 v114, v123
	v_cvt_f32_f16_sdwa v115, v123 dst_sel:DWORD dst_unused:UNUSED_PAD src0_sel:WORD_1
	v_cvt_f32_f16_sdwa v117, v122 dst_sel:DWORD dst_unused:UNUSED_PAD src0_sel:WORD_1
	v_pk_fma_f32 v[110:111], v[110:111], v[50:51], v[114:115]
	v_cvt_f32_f16_e32 v114, v124
	v_cvt_f32_f16_sdwa v115, v124 dst_sel:DWORD dst_unused:UNUSED_PAD src0_sel:WORD_1
	v_pk_fma_f32 v[112:113], v[112:113], v[52:53], v[116:117]
	v_cvt_f32_f16_e32 v116, v125
	v_cvt_f32_f16_sdwa v117, v125 dst_sel:DWORD dst_unused:UNUSED_PAD src0_sel:WORD_1
	v_pk_fma_f32 v[106:107], v[106:107], v[54:55], v[114:115]
	v_cvt_f32_f16_e32 v114, v118
	v_cvt_f32_f16_sdwa v115, v118 dst_sel:DWORD dst_unused:UNUSED_PAD src0_sel:WORD_1
	v_pk_fma_f32 v[108:109], v[108:109], v[56:57], v[116:117]
	v_cvt_f32_f16_e32 v116, v119
	v_cvt_f32_f16_sdwa v117, v119 dst_sel:DWORD dst_unused:UNUSED_PAD src0_sel:WORD_1
	v_pk_fma_f32 v[102:103], v[102:103], v[58:59], v[114:115]
	v_cvt_f32_f16_e32 v114, v120
	v_cvt_f32_f16_sdwa v115, v120 dst_sel:DWORD dst_unused:UNUSED_PAD src0_sel:WORD_1
	v_pk_fma_f32 v[104:105], v[104:105], v[60:61], v[116:117]
	v_cvt_f32_f16_e32 v116, v121
	v_cvt_f32_f16_sdwa v117, v121 dst_sel:DWORD dst_unused:UNUSED_PAD src0_sel:WORD_1
	v_cvt_pk_f16_f32 v122, v110, v111
	v_mov_b32_e32 v118, v1
	v_cvt_pk_f16_f32 v123, v112, v113
	v_pk_fma_f32 v[98:99], v[98:99], v[62:63], v[114:115]
	v_cvt_pk_f16_f32 v115, v102, v103
	v_mov_b32_e32 v114, v1
	v_mov_b32_dpp v118, v122 quad_perm:[1,0,3,2] row_mask:0xf bank_mask:0xf
	v_mov_b32_e32 v119, v1
	v_cvt_pk_f16_f32 v124, v106, v107
	v_pk_fma_f32 v[100:101], v[100:101], v[64:65], v[116:117]
	v_cvt_pk_f16_f32 v116, v104, v105
	v_mov_b32_dpp v114, v115 quad_perm:[1,0,3,2] row_mask:0xf bank_mask:0xf
	v_cndmask_b32_e64 v118, v115, v118, s[0:1]
	v_mov_b32_e32 v115, v1
	v_mov_b32_dpp v119, v123 quad_perm:[1,0,3,2] row_mask:0xf bank_mask:0xf
	v_mov_b32_e32 v120, v1
	v_cvt_pk_f16_f32 v117, v98, v99
	v_mov_b32_dpp v115, v116 quad_perm:[1,0,3,2] row_mask:0xf bank_mask:0xf
	v_cndmask_b32_e64 v119, v116, v119, s[0:1]
	v_mov_b32_e32 v116, v1
	v_mov_b32_dpp v120, v124 quad_perm:[1,0,3,2] row_mask:0xf bank_mask:0xf
	v_cvt_pk_f16_f32 v121, v100, v101
	v_mov_b32_dpp v116, v117 quad_perm:[1,0,3,2] row_mask:0xf bank_mask:0xf
	v_cndmask_b32_e64 v120, v117, v120, s[0:1]
	v_mov_b32_e32 v117, v1
	v_cvt_pk_f16_f32 v125, v108, v109
	v_cndmask_b32_e64 v114, v114, v122, s[0:1]
	v_mov_b32_dpp v117, v121 quad_perm:[1,0,3,2] row_mask:0xf bank_mask:0xf
	v_mov_b32_e32 v122, v1
	v_cndmask_b32_e64 v115, v115, v123, s[0:1]
	v_cndmask_b32_e64 v116, v116, v124, s[0:1]
	v_mov_b32_dpp v122, v125 quad_perm:[1,0,3,2] row_mask:0xf bank_mask:0xf
	v_cndmask_b32_e64 v117, v117, v125, s[0:1]
	v_cndmask_b32_e64 v121, v121, v122, s[0:1]
	global_store_dwordx4 v126, v[114:117], s[38:39]
	s_nop 1
	v_add_u32_e32 v114, 0x16f98800, v0
	global_store_dwordx4 v114, v[118:121], s[38:39]
	s_cbranch_vccnz .LBB0_477
	v_pk_mul_f32 v[114:115], v[32:33], v[100:101]
	v_pk_mul_f32 v[116:117], v[30:31], v[98:99]
	v_cvt_pk_f16_f32 v121, v114, v115
	v_cvt_pk_f16_f32 v120, v116, v117
	v_pk_mul_f32 v[114:115], v[28:29], v[104:105]
	v_pk_mul_f32 v[116:117], v[26:27], v[102:103]
	v_cvt_pk_f16_f32 v119, v114, v115
	v_cvt_pk_f16_f32 v118, v116, v117
	v_pk_mul_f32 v[114:115], v[24:25], v[108:109]
	v_pk_mul_f32 v[116:117], v[22:23], v[106:107]
	v_cvt_pk_f16_f32 v122, v114, v115
	v_cvt_pk_f16_f32 v123, v116, v117
	v_pk_mul_f32 v[114:115], v[20:21], v[112:113]
	v_pk_mul_f32 v[116:117], v[18:19], v[110:111]
	v_cvt_pk_f16_f32 v115, v114, v115
	v_cvt_pk_f16_f32 v114, v116, v117
	v_mov_b32_e32 v117, v1
	v_mov_b32_e32 v116, v1
	v_add_u32_e32 v124, 0x3d98000, v0
	v_mov_b32_dpp v117, v114 quad_perm:[1,0,3,2] row_mask:0xf bank_mask:0xf
	v_mov_b32_dpp v116, v118 quad_perm:[1,0,3,2] row_mask:0xf bank_mask:0xf
	v_cndmask_b32_e64 v118, v118, v117, s[0:1]
	v_mov_b32_e32 v117, v1
	v_cndmask_b32_e64 v114, v116, v114, s[0:1]
	v_mov_b32_e32 v116, v1
	v_mov_b32_dpp v117, v115 quad_perm:[1,0,3,2] row_mask:0xf bank_mask:0xf
	s_nop 0
	v_mov_b32_dpp v116, v119 quad_perm:[1,0,3,2] row_mask:0xf bank_mask:0xf
	v_cndmask_b32_e64 v119, v119, v117, s[0:1]
	v_mov_b32_e32 v117, v1
	v_cndmask_b32_e64 v115, v116, v115, s[0:1]
	v_mov_b32_e32 v116, v1
	v_mov_b32_dpp v117, v123 quad_perm:[1,0,3,2] row_mask:0xf bank_mask:0xf
	s_nop 0
	v_mov_b32_dpp v116, v120 quad_perm:[1,0,3,2] row_mask:0xf bank_mask:0xf
	v_cndmask_b32_e64 v120, v120, v117, s[0:1]
	v_mov_b32_e32 v117, v1
	v_cndmask_b32_e64 v116, v116, v123, s[0:1]
	v_mov_b32_e32 v123, v1
	v_mov_b32_dpp v117, v121 quad_perm:[1,0,3,2] row_mask:0xf bank_mask:0xf
	v_cndmask_b32_e64 v117, v117, v122, s[0:1]
	v_mov_b32_dpp v123, v122 quad_perm:[1,0,3,2] row_mask:0xf bank_mask:0xf
	v_cndmask_b32_e64 v121, v121, v123, s[0:1]
	global_store_dwordx4 v124, v[114:117], s[38:39]
	s_nop 1
	v_add_u32_e32 v114, 0x3d98800, v0
	global_store_dwordx4 v114, v[118:121], s[38:39]

; #define GAS __attribute__((address_space(1)))
; __device__ __forceinline__ unsigned cvtpk_h(float lo, float hi) { f32x2 v = {lo, hi}; h16x2 b = __builtin_convertvector(v, h16x2); return __builtin_bit_cast(unsigned, b); }
;     __device__ __forceinline__ void operator()(const f32x4 (&acc)[2][2][4][2], const pg8::Unit& u, int wr, int wc, int fr, int fq) const {
;     ...
;             for (int m = 0; m < 4; ++m) { if (half && ai == 1) continue; const unsigned rr = (unsigned)(ai * 128 + m * 16); const unsigned o = eoA + rr * (D * 2u); float ss = 0.f;
;                 const u32x4 la = *(const GAS u32x4*)((const GAS char*)ws + (unsigned)WS_X16 + o), lb = *(const GAS u32x4*)((const GAS char*)ws + (unsigned)WS_X16 + o + D * 2u);
;                 u32x4 xr[2];
; #pragma unroll
;                 for (int c = 0; c < 4; ++c) { const unsigned pa = (unsigned)__builtin_amdgcn_update_dpp(0, (int)la[c], 0xB1, 0xF, 0xF, false), pb = (unsigned)__builtin_amdgcn_update_dpp(0, (int)lb[c], 0xB1, 0xF, 0xF, false);
;                     xr[0][c] = odd ? pb : la[c]; xr[1][c] = odd ? lb[c] : pa; }
;                 u32x4 w[2], v[2];
; #pragma unroll
;                 for (int bj = 0; bj < 2; ++bj) { const h16x8 xb = __builtin_bit_cast(h16x8, xr[bj]);
;                     const f32x4 x0 = (f32x4){(float)xb[0], (float)xb[1], (float)xb[2], (float)xb[3]} + g4[bj][0] * acc[ai][bj][m][0], x1 = (f32x4){(float)xb[4], (float)xb[5], (float)xb[6], (float)xb[7]} + g4[bj][1] * acc[ai][bj][m][1];
;                     ss += ((x0[0] * x0[0] + x0[1] * x0[1]) + (x0[2] * x0[2] + x0[3] * x0[3])) + ((x1[0] * x1[0] + x1[1] * x1[1]) + (x1[2] * x1[2] + x1[3] * x1[3]));
;                     w[bj].x = cvtpk_h(x0[0], x0[1]); w[bj].y = cvtpk_h(x0[2], x0[3]); w[bj].z = cvtpk_h(x1[0], x1[1]); w[bj].w = cvtpk_h(x1[2], x1[3]);
;                     const f32x4 y0 = x0 * a4[bj][0], y1 = x1 * a4[bj][1]; v[bj].x = cvtpk_h(y0[0], y0[1]); v[bj].y = cvtpk_h(y0[2], y0[3]); v[bj].z = cvtpk_h(y1[0], y1[1]); v[bj].w = cvtpk_h(y1[2], y1[3]); }
;                 stg_line_pair(ws, (unsigned)WS_X16 + o, D * 2u, w[0], w[1], odd);
;                 if (an_off) stg_line_pair(ws, (unsigned)WS_XS + o, D * 2u, v[0], v[1], odd);
.Lo_wd_4:
	v_mov_b32_e32 v98, v214
	v_mov_b32_e32 v99, v215
	v_mov_b32_e32 v100, v216
	v_mov_b32_e32 v101, v217
	v_mov_b32_e32 v102, v218
	v_mov_b32_e32 v103, v219
	v_mov_b32_e32 v104, v220
	v_mov_b32_e32 v105, v221
	v_add_u32_e32 v222, 0x48000, v0
	global_load_dwordx4 v[214:217], v222, s[42:43]
	global_load_dwordx4 v[218:221], v222, s[42:43] offset:2048
	v_mov_b32_e32 v106, v1
	v_mov_b32_e32 v107, v1
	v_add_u32_e32 v110, 0x16fc0000, v0
	s_and_b64 vcc, exec, s[2:3]
	v_mov_b32_dpp v106, v98 quad_perm:[1,0,3,2] row_mask:0xf bank_mask:0xf
	v_mov_b32_dpp v107, v102 quad_perm:[1,0,3,2] row_mask:0xf bank_mask:0xf
	v_cndmask_b32_e64 v107, v107, v98, s[0:1]
	v_cndmask_b32_e64 v102, v102, v106, s[0:1]
	v_mov_b32_e32 v98, v1
	v_mov_b32_e32 v106, v1
	s_nop 0
	v_mov_b32_dpp v98, v99 quad_perm:[1,0,3,2] row_mask:0xf bank_mask:0xf
	v_mov_b32_dpp v106, v103 quad_perm:[1,0,3,2] row_mask:0xf bank_mask:0xf
	v_cndmask_b32_e64 v106, v106, v99, s[0:1]
	v_cndmask_b32_e64 v103, v103, v98, s[0:1]
	v_mov_b32_e32 v98, v1
	v_mov_b32_e32 v99, v1
	s_nop 0
	v_mov_b32_dpp v98, v100 quad_perm:[1,0,3,2] row_mask:0xf bank_mask:0xf
	v_mov_b32_dpp v99, v104 quad_perm:[1,0,3,2] row_mask:0xf bank_mask:0xf
	v_cndmask_b32_e64 v108, v99, v100, s[0:1]
	v_cndmask_b32_e64 v104, v104, v98, s[0:1]
	v_mov_b32_e32 v98, v1
	v_mov_b32_e32 v99, v1
	v_cvt_f32_f16_e32 v100, v106
	v_mov_b32_dpp v98, v101 quad_perm:[1,0,3,2] row_mask:0xf bank_mask:0xf
	v_mov_b32_dpp v99, v105 quad_perm:[1,0,3,2] row_mask:0xf bank_mask:0xf
	v_cndmask_b32_e64 v109, v99, v101, s[0:1]
	v_cndmask_b32_e64 v105, v105, v98, s[0:1]
	v_cvt_f32_f16_e32 v98, v107
	v_cvt_f32_f16_sdwa v99, v107 dst_sel:DWORD dst_unused:UNUSED_PAD src0_sel:WORD_1
	v_cvt_f32_f16_sdwa v101, v106 dst_sel:DWORD dst_unused:UNUSED_PAD src0_sel:WORD_1
	v_pk_fma_f32 v[94:95], v[94:95], v[50:51], v[98:99]
	v_cvt_f32_f16_e32 v98, v108
	v_cvt_f32_f16_sdwa v99, v108 dst_sel:DWORD dst_unused:UNUSED_PAD src0_sel:WORD_1
	v_pk_fma_f32 v[96:97], v[96:97], v[52:53], v[100:101]
	v_cvt_f32_f16_e32 v100, v109
	v_cvt_f32_f16_sdwa v101, v109 dst_sel:DWORD dst_unused:UNUSED_PAD src0_sel:WORD_1
	v_pk_fma_f32 v[90:91], v[90:91], v[54:55], v[98:99]
	v_cvt_f32_f16_e32 v98, v102
	v_cvt_f32_f16_sdwa v99, v102 dst_sel:DWORD dst_unused:UNUSED_PAD src0_sel:WORD_1
	v_pk_fma_f32 v[92:93], v[92:93], v[56:57], v[100:101]
	v_cvt_f32_f16_e32 v100, v103
	v_cvt_f32_f16_sdwa v101, v103 dst_sel:DWORD dst_unused:UNUSED_PAD src0_sel:WORD_1
	v_pk_fma_f32 v[86:87], v[86:87], v[58:59], v[98:99]
	v_cvt_f32_f16_e32 v98, v104
	v_cvt_f32_f16_sdwa v99, v104 dst_sel:DWORD dst_unused:UNUSED_PAD src0_sel:WORD_1
	v_pk_fma_f32 v[88:89], v[88:89], v[60:61], v[100:101]
	v_cvt_f32_f16_e32 v100, v105
	v_cvt_f32_f16_sdwa v101, v105 dst_sel:DWORD dst_unused:UNUSED_PAD src0_sel:WORD_1
	v_cvt_pk_f16_f32 v106, v94, v95
	v_mov_b32_e32 v102, v1
	v_cvt_pk_f16_f32 v107, v96, v97
	v_pk_fma_f32 v[82:83], v[82:83], v[62:63], v[98:99]
	v_cvt_pk_f16_f32 v99, v86, v87
	v_mov_b32_e32 v98, v1
	v_mov_b32_dpp v102, v106 quad_perm:[1,0,3,2] row_mask:0xf bank_mask:0xf
	v_mov_b32_e32 v103, v1
	v_cvt_pk_f16_f32 v108, v90, v91
	v_pk_fma_f32 v[84:85], v[84:85], v[64:65], v[100:101]
	v_cvt_pk_f16_f32 v100, v88, v89
	v_mov_b32_dpp v98, v99 quad_perm:[1,0,3,2] row_mask:0xf bank_mask:0xf
	v_cndmask_b32_e64 v102, v99, v102, s[0:1]
	v_mov_b32_e32 v99, v1
	v_mov_b32_dpp v103, v107 quad_perm:[1,0,3,2] row_mask:0xf bank_mask:0xf
	v_mov_b32_e32 v104, v1
	v_cvt_pk_f16_f32 v101, v82, v83
	v_mov_b32_dpp v99, v100 quad_perm:[1,0,3,2] row_mask:0xf bank_mask:0xf
	v_cndmask_b32_e64 v103, v100, v103, s[0:1]
	v_mov_b32_e32 v100, v1
	v_mov_b32_dpp v104, v108 quad_perm:[1,0,3,2] row_mask:0xf bank_mask:0xf
	v_cvt_pk_f16_f32 v105, v84, v85
	v_mov_b32_dpp v100, v101 quad_perm:[1,0,3,2] row_mask:0xf bank_mask:0xf
	v_cndmask_b32_e64 v104, v101, v104, s[0:1]
	v_mov_b32_e32 v101, v1
	v_cvt_pk_f16_f32 v109, v92, v93
	v_cndmask_b32_e64 v98, v98, v106, s[0:1]
	v_mov_b32_dpp v101, v105 quad_perm:[1,0,3,2] row_mask:0xf bank_mask:0xf
	v_mov_b32_e32 v106, v1
	v_cndmask_b32_e64 v99, v99, v107, s[0:1]
	v_cndmask_b32_e64 v100, v100, v108, s[0:1]
	v_mov_b32_dpp v106, v109 quad_perm:[1,0,3,2] row_mask:0xf bank_mask:0xf
	v_cndmask_b32_e64 v101, v101, v109, s[0:1]
	v_cndmask_b32_e64 v105, v105, v106, s[0:1]
	global_store_dwordx4 v110, v[98:101], s[38:39]
	s_nop 1
	v_add_u32_e32 v98, 0x16fc0800, v0
	global_store_dwordx4 v98, v[102:105], s[38:39]
	s_cbranch_vccnz .LBB0_481
	v_pk_mul_f32 v[98:99], v[32:33], v[84:85]
	v_pk_mul_f32 v[100:101], v[30:31], v[82:83]
	v_cvt_pk_f16_f32 v105, v98, v99
	v_cvt_pk_f16_f32 v104, v100, v101
	v_pk_mul_f32 v[98:99], v[28:29], v[88:89]
	v_pk_mul_f32 v[100:101], v[26:27], v[86:87]
	v_cvt_pk_f16_f32 v103, v98, v99
	v_cvt_pk_f16_f32 v102, v100, v101
	v_pk_mul_f32 v[98:99], v[24:25], v[92:93]
	v_pk_mul_f32 v[100:101], v[22:23], v[90:91]
	v_cvt_pk_f16_f32 v106, v98, v99
	v_cvt_pk_f16_f32 v107, v100, v101
	v_pk_mul_f32 v[98:99], v[20:21], v[96:97]
	v_pk_mul_f32 v[100:101], v[18:19], v[94:95]
	v_cvt_pk_f16_f32 v99, v98, v99
	v_cvt_pk_f16_f32 v98, v100, v101
	v_mov_b32_e32 v101, v1
	v_mov_b32_e32 v100, v1
	v_add_u32_e32 v108, 0x3dc0000, v0
	v_mov_b32_dpp v101, v98 quad_perm:[1,0,3,2] row_mask:0xf bank_mask:0xf
	v_mov_b32_dpp v100, v102 quad_perm:[1,0,3,2] row_mask:0xf bank_mask:0xf
	v_cndmask_b32_e64 v102, v102, v101, s[0:1]
	v_mov_b32_e32 v101, v1
	v_cndmask_b32_e64 v98, v100, v98, s[0:1]
	v_mov_b32_e32 v100, v1
	v_mov_b32_dpp v101, v99 quad_perm:[1,0,3,2] row_mask:0xf bank_mask:0xf
	s_nop 0
	v_mov_b32_dpp v100, v103 quad_perm:[1,0,3,2] row_mask:0xf bank_mask:0xf
	v_cndmask_b32_e64 v103, v103, v101, s[0:1]
	v_mov_b32_e32 v101, v1
	v_cndmask_b32_e64 v99, v100, v99, s[0:1]
	v_mov_b32_e32 v100, v1
	v_mov_b32_dpp v101, v107 quad_perm:[1,0,3,2] row_mask:0xf bank_mask:0xf
	s_nop 0
	v_mov_b32_dpp v100, v104 quad_perm:[1,0,3,2] row_mask:0xf bank_mask:0xf
	v_cndmask_b32_e64 v104, v104, v101, s[0:1]
	v_mov_b32_e32 v101, v1
	v_cndmask_b32_e64 v100, v100, v107, s[0:1]
	v_mov_b32_e32 v107, v1
	v_mov_b32_dpp v101, v105 quad_perm:[1,0,3,2] row_mask:0xf bank_mask:0xf
	v_cndmask_b32_e64 v101, v101, v106, s[0:1]
	v_mov_b32_dpp v107, v106 quad_perm:[1,0,3,2] row_mask:0xf bank_mask:0xf
	v_cndmask_b32_e64 v105, v105, v107, s[0:1]
	global_store_dwordx4 v108, v[98:101], s[38:39]
	s_nop 1
	v_add_u32_e32 v98, 0x3dc0800, v0
	global_store_dwordx4 v98, v[102:105], s[38:39]

; #define GAS __attribute__((address_space(1)))
; __device__ __forceinline__ unsigned cvtpk_h(float lo, float hi) { f32x2 v = {lo, hi}; h16x2 b = __builtin_convertvector(v, h16x2); return __builtin_bit_cast(unsigned, b); }
;     __device__ __forceinline__ void operator()(const f32x4 (&acc)[2][2][4][2], const pg8::Unit& u, int wr, int wc, int fr, int fq) const {
;     ...
;             for (int m = 0; m < 4; ++m) { if (half && ai == 1) continue; const unsigned rr = (unsigned)(ai * 128 + m * 16); const unsigned o = eoA + rr * (D * 2u); float ss = 0.f;
;                 const u32x4 la = *(const GAS u32x4*)((const GAS char*)ws + (unsigned)WS_X16 + o), lb = *(const GAS u32x4*)((const GAS char*)ws + (unsigned)WS_X16 + o + D * 2u);
;                 u32x4 xr[2];
; #pragma unroll
;                 for (int c = 0; c < 4; ++c) { const unsigned pa = (unsigned)__builtin_amdgcn_update_dpp(0, (int)la[c], 0xB1, 0xF, 0xF, false), pb = (unsigned)__builtin_amdgcn_update_dpp(0, (int)lb[c], 0xB1, 0xF, 0xF, false);
;                     xr[0][c] = odd ? pb : la[c]; xr[1][c] = odd ? lb[c] : pa; }
;                 u32x4 w[2], v[2];
; #pragma unroll
;                 for (int bj = 0; bj < 2; ++bj) { const h16x8 xb = __builtin_bit_cast(h16x8, xr[bj]);
;                     const f32x4 x0 = (f32x4){(float)xb[0], (float)xb[1], (float)xb[2], (float)xb[3]} + g4[bj][0] * acc[ai][bj][m][0], x1 = (f32x4){(float)xb[4], (float)xb[5], (float)xb[6], (float)xb[7]} + g4[bj][1] * acc[ai][bj][m][1];
;                     ss += ((x0[0] * x0[0] + x0[1] * x0[1]) + (x0[2] * x0[2] + x0[3] * x0[3])) + ((x1[0] * x1[0] + x1[1] * x1[1]) + (x1[2] * x1[2] + x1[3] * x1[3]));
;                     w[bj].x = cvtpk_h(x0[0], x0[1]); w[bj].y = cvtpk_h(x0[2], x0[3]); w[bj].z = cvtpk_h(x1[0], x1[1]); w[bj].w = cvtpk_h(x1[2], x1[3]);
;                     const f32x4 y0 = x0 * a4[bj][0], y1 = x1 * a4[bj][1]; v[bj].x = cvtpk_h(y0[0], y0[1]); v[bj].y = cvtpk_h(y0[2], y0[3]); v[bj].z = cvtpk_h(y1[0], y1[1]); v[bj].w = cvtpk_h(y1[2], y1[3]); }
;                 stg_line_pair(ws, (unsigned)WS_X16 + o, D * 2u, w[0], w[1], odd);
;                 if (an_off) stg_line_pair(ws, (unsigned)WS_XS + o, D * 2u, v[0], v[1], odd);
.Lo_wd_5:
	v_mov_b32_e32 v82, v214
	v_mov_b32_e32 v83, v215
	v_mov_b32_e32 v84, v216
	v_mov_b32_e32 v85, v217
	v_mov_b32_e32 v86, v218
	v_mov_b32_e32 v87, v219
	v_mov_b32_e32 v88, v220
	v_mov_b32_e32 v89, v221
	v_add_u32_e32 v222, 0x50000, v0
	global_load_dwordx4 v[214:217], v222, s[42:43]
	global_load_dwordx4 v[218:221], v222, s[42:43] offset:2048
	v_mov_b32_e32 v90, v1
	v_mov_b32_e32 v91, v1
	v_add_u32_e32 v94, 0x16fc8000, v0
	s_and_b64 vcc, exec, s[2:3]
	v_mov_b32_dpp v90, v82 quad_perm:[1,0,3,2] row_mask:0xf bank_mask:0xf
	v_mov_b32_dpp v91, v86 quad_perm:[1,0,3,2] row_mask:0xf bank_mask:0xf
	v_cndmask_b32_e64 v91, v91, v82, s[0:1]
	v_cndmask_b32_e64 v86, v86, v90, s[0:1]
	v_mov_b32_e32 v82, v1
	v_mov_b32_e32 v90, v1
	s_nop 0
	v_mov_b32_dpp v82, v83 quad_perm:[1,0,3,2] row_mask:0xf bank_mask:0xf
	v_mov_b32_dpp v90, v87 quad_perm:[1,0,3,2] row_mask:0xf bank_mask:0xf
	v_cndmask_b32_e64 v90, v90, v83, s[0:1]
	v_cndmask_b32_e64 v87, v87, v82, s[0:1]
	v_mov_b32_e32 v82, v1
	v_mov_b32_e32 v83, v1
	s_nop 0
	v_mov_b32_dpp v82, v84 quad_perm:[1,0,3,2] row_mask:0xf bank_mask:0xf
	v_mov_b32_dpp v83, v88 quad_perm:[1,0,3,2] row_mask:0xf bank_mask:0xf
	v_cndmask_b32_e64 v92, v83, v84, s[0:1]
	v_cndmask_b32_e64 v88, v88, v82, s[0:1]
	v_mov_b32_e32 v82, v1
	v_mov_b32_e32 v83, v1
	v_cvt_f32_f16_e32 v84, v90
	v_mov_b32_dpp v82, v85 quad_perm:[1,0,3,2] row_mask:0xf bank_mask:0xf
	v_mov_b32_dpp v83, v89 quad_perm:[1,0,3,2] row_mask:0xf bank_mask:0xf
	v_cndmask_b32_e64 v93, v83, v85, s[0:1]
	v_cndmask_b32_e64 v89, v89, v82, s[0:1]
	v_cvt_f32_f16_e32 v82, v91
	v_cvt_f32_f16_sdwa v83, v91 dst_sel:DWORD dst_unused:UNUSED_PAD src0_sel:WORD_1
	v_cvt_f32_f16_sdwa v85, v90 dst_sel:DWORD dst_unused:UNUSED_PAD src0_sel:WORD_1
	v_pk_fma_f32 v[78:79], v[78:79], v[50:51], v[82:83]
	v_cvt_f32_f16_e32 v82, v92
	v_cvt_f32_f16_sdwa v83, v92 dst_sel:DWORD dst_unused:UNUSED_PAD src0_sel:WORD_1
	v_pk_fma_f32 v[80:81], v[80:81], v[52:53], v[84:85]
	v_cvt_f32_f16_e32 v84, v93
	v_cvt_f32_f16_sdwa v85, v93 dst_sel:DWORD dst_unused:UNUSED_PAD src0_sel:WORD_1
	v_pk_fma_f32 v[74:75], v[74:75], v[54:55], v[82:83]
	v_cvt_f32_f16_e32 v82, v86
	v_cvt_f32_f16_sdwa v83, v86 dst_sel:DWORD dst_unused:UNUSED_PAD src0_sel:WORD_1
	v_pk_fma_f32 v[76:77], v[76:77], v[56:57], v[84:85]
	v_cvt_f32_f16_e32 v84, v87
	v_cvt_f32_f16_sdwa v85, v87 dst_sel:DWORD dst_unused:UNUSED_PAD src0_sel:WORD_1
	v_pk_fma_f32 v[70:71], v[70:71], v[58:59], v[82:83]
	v_cvt_f32_f16_e32 v82, v88
	v_cvt_f32_f16_sdwa v83, v88 dst_sel:DWORD dst_unused:UNUSED_PAD src0_sel:WORD_1
	v_pk_fma_f32 v[72:73], v[72:73], v[60:61], v[84:85]
	v_cvt_f32_f16_e32 v84, v89
	v_cvt_f32_f16_sdwa v85, v89 dst_sel:DWORD dst_unused:UNUSED_PAD src0_sel:WORD_1
	v_cvt_pk_f16_f32 v90, v78, v79
	v_mov_b32_e32 v86, v1
	v_cvt_pk_f16_f32 v91, v80, v81
	v_pk_fma_f32 v[66:67], v[66:67], v[62:63], v[82:83]
	v_cvt_pk_f16_f32 v83, v70, v71
	v_mov_b32_e32 v82, v1
	v_mov_b32_dpp v86, v90 quad_perm:[1,0,3,2] row_mask:0xf bank_mask:0xf
	v_mov_b32_e32 v87, v1
	v_cvt_pk_f16_f32 v92, v74, v75
	v_pk_fma_f32 v[68:69], v[68:69], v[64:65], v[84:85]
	v_cvt_pk_f16_f32 v84, v72, v73
	v_mov_b32_dpp v82, v83 quad_perm:[1,0,3,2] row_mask:0xf bank_mask:0xf
	v_cndmask_b32_e64 v86, v83, v86, s[0:1]
	v_mov_b32_e32 v83, v1
	v_mov_b32_dpp v87, v91 quad_perm:[1,0,3,2] row_mask:0xf bank_mask:0xf
	v_mov_b32_e32 v88, v1
	v_cvt_pk_f16_f32 v85, v66, v67
	v_mov_b32_dpp v83, v84 quad_perm:[1,0,3,2] row_mask:0xf bank_mask:0xf
	v_cndmask_b32_e64 v87, v84, v87, s[0:1]
	v_mov_b32_e32 v84, v1
	v_mov_b32_dpp v88, v92 quad_perm:[1,0,3,2] row_mask:0xf bank_mask:0xf
	v_cvt_pk_f16_f32 v89, v68, v69
	v_mov_b32_dpp v84, v85 quad_perm:[1,0,3,2] row_mask:0xf bank_mask:0xf
	v_cndmask_b32_e64 v88, v85, v88, s[0:1]
	v_mov_b32_e32 v85, v1
	v_cvt_pk_f16_f32 v93, v76, v77
	v_cndmask_b32_e64 v82, v82, v90, s[0:1]
	v_mov_b32_dpp v85, v89 quad_perm:[1,0,3,2] row_mask:0xf bank_mask:0xf
	v_mov_b32_e32 v90, v1
	v_cndmask_b32_e64 v83, v83, v91, s[0:1]
	v_cndmask_b32_e64 v84, v84, v92, s[0:1]
	v_mov_b32_dpp v90, v93 quad_perm:[1,0,3,2] row_mask:0xf bank_mask:0xf
	v_cndmask_b32_e64 v85, v85, v93, s[0:1]
	v_cndmask_b32_e64 v89, v89, v90, s[0:1]
	global_store_dwordx4 v94, v[82:85], s[38:39]
	s_nop 1
	v_add_u32_e32 v82, 0x16fc8800, v0
	global_store_dwordx4 v82, v[86:89], s[38:39]
	s_cbranch_vccnz .LBB0_485
	v_pk_mul_f32 v[82:83], v[32:33], v[68:69]
	v_pk_mul_f32 v[84:85], v[30:31], v[66:67]
	v_cvt_pk_f16_f32 v89, v82, v83
	v_cvt_pk_f16_f32 v88, v84, v85
	v_pk_mul_f32 v[82:83], v[28:29], v[72:73]
	v_pk_mul_f32 v[84:85], v[26:27], v[70:71]
	v_cvt_pk_f16_f32 v87, v82, v83
	v_cvt_pk_f16_f32 v86, v84, v85
	v_pk_mul_f32 v[82:83], v[24:25], v[76:77]
	v_pk_mul_f32 v[84:85], v[22:23], v[74:75]
	v_cvt_pk_f16_f32 v90, v82, v83
	v_cvt_pk_f16_f32 v91, v84, v85
	v_pk_mul_f32 v[82:83], v[20:21], v[80:81]
	v_pk_mul_f32 v[84:85], v[18:19], v[78:79]
	v_cvt_pk_f16_f32 v83, v82, v83
	v_cvt_pk_f16_f32 v82, v84, v85
	v_mov_b32_e32 v85, v1
	v_mov_b32_e32 v84, v1
	v_add_u32_e32 v92, 0x3dc8000, v0
	v_mov_b32_dpp v85, v82 quad_perm:[1,0,3,2] row_mask:0xf bank_mask:0xf
	v_mov_b32_dpp v84, v86 quad_perm:[1,0,3,2] row_mask:0xf bank_mask:0xf
	v_cndmask_b32_e64 v86, v86, v85, s[0:1]
	v_mov_b32_e32 v85, v1
	v_cndmask_b32_e64 v82, v84, v82, s[0:1]
	v_mov_b32_e32 v84, v1
	v_mov_b32_dpp v85, v83 quad_perm:[1,0,3,2] row_mask:0xf bank_mask:0xf
	s_nop 0
	v_mov_b32_dpp v84, v87 quad_perm:[1,0,3,2] row_mask:0xf bank_mask:0xf
	v_cndmask_b32_e64 v87, v87, v85, s[0:1]
	v_mov_b32_e32 v85, v1
	v_cndmask_b32_e64 v83, v84, v83, s[0:1]
	v_mov_b32_e32 v84, v1
	v_mov_b32_dpp v85, v91 quad_perm:[1,0,3,2] row_mask:0xf bank_mask:0xf
	s_nop 0
	v_mov_b32_dpp v84, v88 quad_perm:[1,0,3,2] row_mask:0xf bank_mask:0xf
	v_cndmask_b32_e64 v88, v88, v85, s[0:1]
	v_mov_b32_e32 v85, v1
	v_cndmask_b32_e64 v84, v84, v91, s[0:1]
	v_mov_b32_e32 v91, v1
	v_mov_b32_dpp v85, v89 quad_perm:[1,0,3,2] row_mask:0xf bank_mask:0xf
	v_cndmask_b32_e64 v85, v85, v90, s[0:1]
	v_mov_b32_dpp v91, v90 quad_perm:[1,0,3,2] row_mask:0xf bank_mask:0xf
	v_cndmask_b32_e64 v89, v89, v91, s[0:1]
	global_store_dwordx4 v92, v[82:85], s[38:39]
	s_nop 1
	v_add_u32_e32 v82, 0x3dc8800, v0
	global_store_dwordx4 v82, v[86:89], s[38:39]

; #define GAS __attribute__((address_space(1)))
; __device__ __forceinline__ unsigned cvtpk_h(float lo, float hi) { f32x2 v = {lo, hi}; h16x2 b = __builtin_convertvector(v, h16x2); return __builtin_bit_cast(unsigned, b); }
;     __device__ __forceinline__ void operator()(const f32x4 (&acc)[2][2][4][2], const pg8::Unit& u, int wr, int wc, int fr, int fq) const {
;     ...
;             for (int m = 0; m < 4; ++m) { if (half && ai == 1) continue; const unsigned rr = (unsigned)(ai * 128 + m * 16); const unsigned o = eoA + rr * (D * 2u); float ss = 0.f;
;                 const u32x4 la = *(const GAS u32x4*)((const GAS char*)ws + (unsigned)WS_X16 + o), lb = *(const GAS u32x4*)((const GAS char*)ws + (unsigned)WS_X16 + o + D * 2u);
;                 u32x4 xr[2];
; #pragma unroll
;                 for (int c = 0; c < 4; ++c) { const unsigned pa = (unsigned)__builtin_amdgcn_update_dpp(0, (int)la[c], 0xB1, 0xF, 0xF, false), pb = (unsigned)__builtin_amdgcn_update_dpp(0, (int)lb[c], 0xB1, 0xF, 0xF, false);
;                     xr[0][c] = odd ? pb : la[c]; xr[1][c] = odd ? lb[c] : pa; }
;                 u32x4 w[2], v[2];
; #pragma unroll
;                 for (int bj = 0; bj < 2; ++bj) { const h16x8 xb = __builtin_bit_cast(h16x8, xr[bj]);
;                     const f32x4 x0 = (f32x4){(float)xb[0], (float)xb[1], (float)xb[2], (float)xb[3]} + g4[bj][0] * acc[ai][bj][m][0], x1 = (f32x4){(float)xb[4], (float)xb[5], (float)xb[6], (float)xb[7]} + g4[bj][1] * acc[ai][bj][m][1];
;                     ss += ((x0[0] * x0[0] + x0[1] * x0[1]) + (x0[2] * x0[2] + x0[3] * x0[3])) + ((x1[0] * x1[0] + x1[1] * x1[1]) + (x1[2] * x1[2] + x1[3] * x1[3]));
;                     w[bj].x = cvtpk_h(x0[0], x0[1]); w[bj].y = cvtpk_h(x0[2], x0[3]); w[bj].z = cvtpk_h(x1[0], x1[1]); w[bj].w = cvtpk_h(x1[2], x1[3]);
;                     const f32x4 y0 = x0 * a4[bj][0], y1 = x1 * a4[bj][1]; v[bj].x = cvtpk_h(y0[0], y0[1]); v[bj].y = cvtpk_h(y0[2], y0[3]); v[bj].z = cvtpk_h(y1[0], y1[1]); v[bj].w = cvtpk_h(y1[2], y1[3]); }
;                 stg_line_pair(ws, (unsigned)WS_X16 + o, D * 2u, w[0], w[1], odd);
;                 if (an_off) stg_line_pair(ws, (unsigned)WS_XS + o, D * 2u, v[0], v[1], odd);
.Lo_wd_6:
	v_mov_b32_e32 v66, v214
	v_mov_b32_e32 v67, v215
	v_mov_b32_e32 v68, v216
	v_mov_b32_e32 v69, v217
	v_mov_b32_e32 v70, v218
	v_mov_b32_e32 v71, v219
	v_mov_b32_e32 v72, v220
	v_mov_b32_e32 v73, v221
	v_add_u32_e32 v222, 0x58000, v0
	global_load_dwordx4 v[214:217], v222, s[42:43]
	global_load_dwordx4 v[218:221], v222, s[42:43] offset:2048
	v_mov_b32_e32 v74, v1
	v_mov_b32_e32 v75, v1
	v_add_u32_e32 v78, 0x16fd0000, v0
	s_and_b64 vcc, exec, s[2:3]
	v_mov_b32_dpp v74, v66 quad_perm:[1,0,3,2] row_mask:0xf bank_mask:0xf
	v_mov_b32_dpp v75, v70 quad_perm:[1,0,3,2] row_mask:0xf bank_mask:0xf
	v_cndmask_b32_e64 v75, v75, v66, s[0:1]
	v_cndmask_b32_e64 v70, v70, v74, s[0:1]
	v_mov_b32_e32 v66, v1
	v_mov_b32_e32 v74, v1
	s_nop 0
	v_mov_b32_dpp v66, v67 quad_perm:[1,0,3,2] row_mask:0xf bank_mask:0xf
	v_mov_b32_dpp v74, v71 quad_perm:[1,0,3,2] row_mask:0xf bank_mask:0xf
	v_cndmask_b32_e64 v74, v74, v67, s[0:1]
	v_cndmask_b32_e64 v71, v71, v66, s[0:1]
	v_mov_b32_e32 v66, v1
	v_mov_b32_e32 v67, v1
	s_nop 0
	v_mov_b32_dpp v66, v68 quad_perm:[1,0,3,2] row_mask:0xf bank_mask:0xf
	v_mov_b32_dpp v67, v72 quad_perm:[1,0,3,2] row_mask:0xf bank_mask:0xf
	v_cndmask_b32_e64 v76, v67, v68, s[0:1]
	v_cndmask_b32_e64 v72, v72, v66, s[0:1]
	v_mov_b32_e32 v66, v1
	v_mov_b32_e32 v67, v1
	v_cvt_f32_f16_e32 v68, v74
	v_mov_b32_dpp v66, v69 quad_perm:[1,0,3,2] row_mask:0xf bank_mask:0xf
	v_mov_b32_dpp v67, v73 quad_perm:[1,0,3,2] row_mask:0xf bank_mask:0xf
	v_cndmask_b32_e64 v77, v67, v69, s[0:1]
	v_cndmask_b32_e64 v73, v73, v66, s[0:1]
	v_cvt_f32_f16_e32 v66, v75
	v_cvt_f32_f16_sdwa v67, v75 dst_sel:DWORD dst_unused:UNUSED_PAD src0_sel:WORD_1
	v_cvt_f32_f16_sdwa v69, v74 dst_sel:DWORD dst_unused:UNUSED_PAD src0_sel:WORD_1
	v_pk_fma_f32 v[46:47], v[46:47], v[50:51], v[66:67]
	v_cvt_f32_f16_e32 v66, v76
	v_cvt_f32_f16_sdwa v67, v76 dst_sel:DWORD dst_unused:UNUSED_PAD src0_sel:WORD_1
	v_pk_fma_f32 v[48:49], v[48:49], v[52:53], v[68:69]
	v_cvt_f32_f16_e32 v68, v77
	v_cvt_f32_f16_sdwa v69, v77 dst_sel:DWORD dst_unused:UNUSED_PAD src0_sel:WORD_1
	v_pk_fma_f32 v[42:43], v[42:43], v[54:55], v[66:67]
	v_cvt_f32_f16_e32 v66, v70
	v_cvt_f32_f16_sdwa v67, v70 dst_sel:DWORD dst_unused:UNUSED_PAD src0_sel:WORD_1
	v_pk_fma_f32 v[44:45], v[44:45], v[56:57], v[68:69]
	v_cvt_f32_f16_e32 v68, v71
	v_cvt_f32_f16_sdwa v69, v71 dst_sel:DWORD dst_unused:UNUSED_PAD src0_sel:WORD_1
	v_pk_fma_f32 v[38:39], v[38:39], v[58:59], v[66:67]
	v_cvt_f32_f16_e32 v66, v72
	v_cvt_f32_f16_sdwa v67, v72 dst_sel:DWORD dst_unused:UNUSED_PAD src0_sel:WORD_1
	v_pk_fma_f32 v[40:41], v[40:41], v[60:61], v[68:69]
	v_cvt_f32_f16_e32 v68, v73
	v_cvt_f32_f16_sdwa v69, v73 dst_sel:DWORD dst_unused:UNUSED_PAD src0_sel:WORD_1
	v_cvt_pk_f16_f32 v74, v46, v47
	v_mov_b32_e32 v70, v1
	v_cvt_pk_f16_f32 v75, v48, v49
	v_pk_fma_f32 v[34:35], v[34:35], v[62:63], v[66:67]
	v_cvt_pk_f16_f32 v67, v38, v39
	v_mov_b32_e32 v66, v1
	v_mov_b32_dpp v70, v74 quad_perm:[1,0,3,2] row_mask:0xf bank_mask:0xf
	v_mov_b32_e32 v71, v1
	v_cvt_pk_f16_f32 v76, v42, v43
	v_pk_fma_f32 v[36:37], v[36:37], v[64:65], v[68:69]
	v_cvt_pk_f16_f32 v68, v40, v41
	v_mov_b32_dpp v66, v67 quad_perm:[1,0,3,2] row_mask:0xf bank_mask:0xf
	v_cndmask_b32_e64 v70, v67, v70, s[0:1]
	v_mov_b32_e32 v67, v1
	v_mov_b32_dpp v71, v75 quad_perm:[1,0,3,2] row_mask:0xf bank_mask:0xf
	v_mov_b32_e32 v72, v1
	v_cvt_pk_f16_f32 v69, v34, v35
	v_mov_b32_dpp v67, v68 quad_perm:[1,0,3,2] row_mask:0xf bank_mask:0xf
	v_cndmask_b32_e64 v71, v68, v71, s[0:1]
	v_mov_b32_e32 v68, v1
	v_mov_b32_dpp v72, v76 quad_perm:[1,0,3,2] row_mask:0xf bank_mask:0xf
	v_cvt_pk_f16_f32 v73, v36, v37
	v_mov_b32_dpp v68, v69 quad_perm:[1,0,3,2] row_mask:0xf bank_mask:0xf
	v_cndmask_b32_e64 v72, v69, v72, s[0:1]
	v_mov_b32_e32 v69, v1
	v_cvt_pk_f16_f32 v77, v44, v45
	v_cndmask_b32_e64 v66, v66, v74, s[0:1]
	v_mov_b32_dpp v69, v73 quad_perm:[1,0,3,2] row_mask:0xf bank_mask:0xf
	v_mov_b32_e32 v74, v1
	v_cndmask_b32_e64 v67, v67, v75, s[0:1]
	v_cndmask_b32_e64 v68, v68, v76, s[0:1]
	v_mov_b32_dpp v74, v77 quad_perm:[1,0,3,2] row_mask:0xf bank_mask:0xf
	v_cndmask_b32_e64 v69, v69, v77, s[0:1]
	v_cndmask_b32_e64 v73, v73, v74, s[0:1]
	global_store_dwordx4 v78, v[66:69], s[38:39]
	s_nop 1
	v_add_u32_e32 v66, 0x16fd0800, v0
	global_store_dwordx4 v66, v[70:73], s[38:39]
	s_cbranch_vccnz .LBB0_489
	v_pk_mul_f32 v[66:67], v[32:33], v[36:37]
	v_pk_mul_f32 v[68:69], v[30:31], v[34:35]
	v_cvt_pk_f16_f32 v73, v66, v67
	v_cvt_pk_f16_f32 v72, v68, v69
	v_pk_mul_f32 v[66:67], v[28:29], v[40:41]
	v_pk_mul_f32 v[68:69], v[26:27], v[38:39]
	v_cvt_pk_f16_f32 v71, v66, v67
	v_cvt_pk_f16_f32 v70, v68, v69
	v_pk_mul_f32 v[66:67], v[24:25], v[44:45]
	v_pk_mul_f32 v[68:69], v[22:23], v[42:43]
	v_cvt_pk_f16_f32 v74, v66, v67
	v_cvt_pk_f16_f32 v75, v68, v69
	v_pk_mul_f32 v[66:67], v[20:21], v[48:49]
	v_pk_mul_f32 v[68:69], v[18:19], v[46:47]
	v_cvt_pk_f16_f32 v67, v66, v67
	v_cvt_pk_f16_f32 v66, v68, v69
	v_mov_b32_e32 v69, v1
	v_mov_b32_e32 v68, v1
	v_add_u32_e32 v76, 0x3dd0000, v0
	v_mov_b32_dpp v69, v66 quad_perm:[1,0,3,2] row_mask:0xf bank_mask:0xf
	v_mov_b32_dpp v68, v70 quad_perm:[1,0,3,2] row_mask:0xf bank_mask:0xf
	v_cndmask_b32_e64 v70, v70, v69, s[0:1]
	v_mov_b32_e32 v69, v1
	v_cndmask_b32_e64 v66, v68, v66, s[0:1]
	v_mov_b32_e32 v68, v1
	v_mov_b32_dpp v69, v67 quad_perm:[1,0,3,2] row_mask:0xf bank_mask:0xf
	s_nop 0
	v_mov_b32_dpp v68, v71 quad_perm:[1,0,3,2] row_mask:0xf bank_mask:0xf
	v_cndmask_b32_e64 v71, v71, v69, s[0:1]
	v_mov_b32_e32 v69, v1
	v_cndmask_b32_e64 v67, v68, v67, s[0:1]
	v_mov_b32_e32 v68, v1
	v_mov_b32_dpp v69, v75 quad_perm:[1,0,3,2] row_mask:0xf bank_mask:0xf
	s_nop 0
	v_mov_b32_dpp v68, v72 quad_perm:[1,0,3,2] row_mask:0xf bank_mask:0xf
	v_cndmask_b32_e64 v72, v72, v69, s[0:1]
	v_mov_b32_e32 v69, v1
	v_cndmask_b32_e64 v68, v68, v75, s[0:1]
	v_mov_b32_e32 v75, v1
	v_mov_b32_dpp v69, v73 quad_perm:[1,0,3,2] row_mask:0xf bank_mask:0xf
	v_cndmask_b32_e64 v69, v69, v74, s[0:1]
	v_mov_b32_dpp v75, v74 quad_perm:[1,0,3,2] row_mask:0xf bank_mask:0xf
	v_cndmask_b32_e64 v73, v73, v75, s[0:1]
	global_store_dwordx4 v76, v[66:69], s[38:39]
	s_nop 1
	v_add_u32_e32 v66, 0x3dd0800, v0
	global_store_dwordx4 v66, v[70:73], s[38:39]

; #define GAS __attribute__((address_space(1)))
; __device__ __forceinline__ unsigned cvtpk_h(float lo, float hi) { f32x2 v = {lo, hi}; h16x2 b = __builtin_convertvector(v, h16x2); return __builtin_bit_cast(unsigned, b); }
;     __device__ __forceinline__ void operator()(const f32x4 (&acc)[2][2][4][2], const pg8::Unit& u, int wr, int wc, int fr, int fq) const {
;     ...
;             for (int m = 0; m < 4; ++m) { if (half && ai == 1) continue; const unsigned rr = (unsigned)(ai * 128 + m * 16); const unsigned o = eoA + rr * (D * 2u); float ss = 0.f;
;                 const u32x4 la = *(const GAS u32x4*)((const GAS char*)ws + (unsigned)WS_X16 + o), lb = *(const GAS u32x4*)((const GAS char*)ws + (unsigned)WS_X16 + o + D * 2u);
;                 u32x4 xr[2];
; #pragma unroll
;                 for (int c = 0; c < 4; ++c) { const unsigned pa = (unsigned)__builtin_amdgcn_update_dpp(0, (int)la[c], 0xB1, 0xF, 0xF, false), pb = (unsigned)__builtin_amdgcn_update_dpp(0, (int)lb[c], 0xB1, 0xF, 0xF, false);
;                     xr[0][c] = odd ? pb : la[c]; xr[1][c] = odd ? lb[c] : pa; }
;                 u32x4 w[2], v[2];
; #pragma unroll
;                 for (int bj = 0; bj < 2; ++bj) { const h16x8 xb = __builtin_bit_cast(h16x8, xr[bj]);
;                     const f32x4 x0 = (f32x4){(float)xb[0], (float)xb[1], (float)xb[2], (float)xb[3]} + g4[bj][0] * acc[ai][bj][m][0], x1 = (f32x4){(float)xb[4], (float)xb[5], (float)xb[6], (float)xb[7]} + g4[bj][1] * acc[ai][bj][m][1];
;                     ss += ((x0[0] * x0[0] + x0[1] * x0[1]) + (x0[2] * x0[2] + x0[3] * x0[3])) + ((x1[0] * x1[0] + x1[1] * x1[1]) + (x1[2] * x1[2] + x1[3] * x1[3]));
;                     w[bj].x = cvtpk_h(x0[0], x0[1]); w[bj].y = cvtpk_h(x0[2], x0[3]); w[bj].z = cvtpk_h(x1[0], x1[1]); w[bj].w = cvtpk_h(x1[2], x1[3]);
;                     const f32x4 y0 = x0 * a4[bj][0], y1 = x1 * a4[bj][1]; v[bj].x = cvtpk_h(y0[0], y0[1]); v[bj].y = cvtpk_h(y0[2], y0[3]); v[bj].z = cvtpk_h(y1[0], y1[1]); v[bj].w = cvtpk_h(y1[2], y1[3]); }
;                 stg_line_pair(ws, (unsigned)WS_X16 + o, D * 2u, w[0], w[1], odd);
;                 if (an_off) stg_line_pair(ws, (unsigned)WS_XS + o, D * 2u, v[0], v[1], odd);
.Lo_wd_7:
	v_mov_b32_e32 v34, v214
	v_mov_b32_e32 v35, v215
	v_mov_b32_e32 v36, v216
	v_mov_b32_e32 v37, v217
	v_mov_b32_e32 v38, v218
	v_mov_b32_e32 v39, v219
	v_mov_b32_e32 v40, v220
	v_mov_b32_e32 v41, v221
	v_mov_b32_e32 v42, v1
	v_mov_b32_e32 v43, v1
	v_add_u32_e32 v46, 0x16fd8000, v0
	s_and_b64 vcc, exec, s[2:3]
	v_mov_b32_dpp v42, v34 quad_perm:[1,0,3,2] row_mask:0xf bank_mask:0xf
	v_mov_b32_dpp v43, v38 quad_perm:[1,0,3,2] row_mask:0xf bank_mask:0xf
	v_cndmask_b32_e64 v43, v43, v34, s[0:1]
	v_cndmask_b32_e64 v38, v38, v42, s[0:1]
	v_mov_b32_e32 v34, v1
	v_mov_b32_e32 v42, v1
	s_nop 0
	v_mov_b32_dpp v34, v35 quad_perm:[1,0,3,2] row_mask:0xf bank_mask:0xf
	v_mov_b32_dpp v42, v39 quad_perm:[1,0,3,2] row_mask:0xf bank_mask:0xf
	v_cndmask_b32_e64 v42, v42, v35, s[0:1]
	v_cndmask_b32_e64 v39, v39, v34, s[0:1]
	v_mov_b32_e32 v34, v1
	v_mov_b32_e32 v35, v1
	s_nop 0
	v_mov_b32_dpp v34, v36 quad_perm:[1,0,3,2] row_mask:0xf bank_mask:0xf
	v_mov_b32_dpp v35, v40 quad_perm:[1,0,3,2] row_mask:0xf bank_mask:0xf
	v_cndmask_b32_e64 v44, v35, v36, s[0:1]
	v_cndmask_b32_e64 v40, v40, v34, s[0:1]
	v_mov_b32_e32 v34, v1
	v_mov_b32_e32 v35, v1
	v_cvt_f32_f16_e32 v36, v42
	v_mov_b32_dpp v34, v37 quad_perm:[1,0,3,2] row_mask:0xf bank_mask:0xf
	v_mov_b32_dpp v35, v41 quad_perm:[1,0,3,2] row_mask:0xf bank_mask:0xf
	v_cndmask_b32_e64 v45, v35, v37, s[0:1]
	v_cndmask_b32_e64 v41, v41, v34, s[0:1]
	v_cvt_f32_f16_e32 v34, v43
	v_cvt_f32_f16_sdwa v35, v43 dst_sel:DWORD dst_unused:UNUSED_PAD src0_sel:WORD_1
	v_cvt_f32_f16_sdwa v37, v42 dst_sel:DWORD dst_unused:UNUSED_PAD src0_sel:WORD_1
	v_pk_fma_f32 v[14:15], v[14:15], v[50:51], v[34:35]
	v_cvt_f32_f16_e32 v34, v44
	v_cvt_f32_f16_sdwa v35, v44 dst_sel:DWORD dst_unused:UNUSED_PAD src0_sel:WORD_1
	v_pk_fma_f32 v[16:17], v[16:17], v[52:53], v[36:37]
	v_cvt_f32_f16_e32 v36, v45
	v_cvt_f32_f16_sdwa v37, v45 dst_sel:DWORD dst_unused:UNUSED_PAD src0_sel:WORD_1
	v_pk_fma_f32 v[10:11], v[10:11], v[54:55], v[34:35]
	v_cvt_f32_f16_e32 v34, v38
	v_cvt_f32_f16_sdwa v35, v38 dst_sel:DWORD dst_unused:UNUSED_PAD src0_sel:WORD_1
	v_pk_fma_f32 v[12:13], v[12:13], v[56:57], v[36:37]
	v_cvt_f32_f16_e32 v36, v39
	v_cvt_f32_f16_sdwa v37, v39 dst_sel:DWORD dst_unused:UNUSED_PAD src0_sel:WORD_1
	v_pk_fma_f32 v[6:7], v[6:7], v[58:59], v[34:35]
	v_cvt_f32_f16_e32 v34, v40
	v_cvt_f32_f16_sdwa v35, v40 dst_sel:DWORD dst_unused:UNUSED_PAD src0_sel:WORD_1
	v_pk_fma_f32 v[8:9], v[8:9], v[60:61], v[36:37]
	v_cvt_f32_f16_e32 v36, v41
	v_cvt_f32_f16_sdwa v37, v41 dst_sel:DWORD dst_unused:UNUSED_PAD src0_sel:WORD_1
	v_cvt_pk_f16_f32 v42, v14, v15
	v_mov_b32_e32 v38, v1
	v_cvt_pk_f16_f32 v43, v16, v17
	v_pk_fma_f32 v[2:3], v[2:3], v[62:63], v[34:35]
	v_cvt_pk_f16_f32 v35, v6, v7
	v_mov_b32_e32 v34, v1
	v_mov_b32_dpp v38, v42 quad_perm:[1,0,3,2] row_mask:0xf bank_mask:0xf
	v_mov_b32_e32 v39, v1
	v_cvt_pk_f16_f32 v44, v10, v11
	v_pk_fma_f32 v[4:5], v[4:5], v[64:65], v[36:37]
	v_cvt_pk_f16_f32 v36, v8, v9
	v_mov_b32_dpp v34, v35 quad_perm:[1,0,3,2] row_mask:0xf bank_mask:0xf
	v_cndmask_b32_e64 v38, v35, v38, s[0:1]
	v_mov_b32_e32 v35, v1
	v_mov_b32_dpp v39, v43 quad_perm:[1,0,3,2] row_mask:0xf bank_mask:0xf
	v_mov_b32_e32 v40, v1
	v_cvt_pk_f16_f32 v37, v2, v3
	v_mov_b32_dpp v35, v36 quad_perm:[1,0,3,2] row_mask:0xf bank_mask:0xf
	v_cndmask_b32_e64 v39, v36, v39, s[0:1]
	v_mov_b32_e32 v36, v1
	v_mov_b32_dpp v40, v44 quad_perm:[1,0,3,2] row_mask:0xf bank_mask:0xf
	v_cvt_pk_f16_f32 v41, v4, v5
	v_mov_b32_dpp v36, v37 quad_perm:[1,0,3,2] row_mask:0xf bank_mask:0xf
	v_cndmask_b32_e64 v40, v37, v40, s[0:1]
	v_mov_b32_e32 v37, v1
	v_cvt_pk_f16_f32 v45, v12, v13
	v_cndmask_b32_e64 v34, v34, v42, s[0:1]
	v_mov_b32_dpp v37, v41 quad_perm:[1,0,3,2] row_mask:0xf bank_mask:0xf
	v_mov_b32_e32 v42, v1
	v_cndmask_b32_e64 v35, v35, v43, s[0:1]
	v_cndmask_b32_e64 v36, v36, v44, s[0:1]
	v_mov_b32_dpp v42, v45 quad_perm:[1,0,3,2] row_mask:0xf bank_mask:0xf
	v_cndmask_b32_e64 v37, v37, v45, s[0:1]
	v_cndmask_b32_e64 v41, v41, v42, s[0:1]
	global_store_dwordx4 v46, v[34:37], s[38:39]
	s_nop 1
	v_add_u32_e32 v34, 0x16fd8800, v0
	global_store_dwordx4 v34, v[38:41], s[38:39]
	s_cbranch_vccnz .LBB0_493
	v_pk_mul_f32 v[26:27], v[26:27], v[6:7]
	v_pk_mul_f32 v[20:21], v[20:21], v[16:17]
	v_pk_mul_f32 v[18:19], v[18:19], v[14:15]
	v_cvt_pk_f16_f32 v26, v26, v27
	v_cvt_pk_f16_f32 v20, v20, v21
	v_cvt_pk_f16_f32 v18, v18, v19
	v_mov_b32_e32 v19, v1
	v_mov_b32_e32 v21, v1
	v_pk_mul_f32 v[28:29], v[28:29], v[8:9]
	v_pk_mul_f32 v[24:25], v[24:25], v[12:13]
	v_pk_mul_f32 v[22:23], v[22:23], v[10:11]
	v_mov_b32_dpp v19, v26 quad_perm:[1,0,3,2] row_mask:0xf bank_mask:0xf
	v_mov_b32_dpp v21, v18 quad_perm:[1,0,3,2] row_mask:0xf bank_mask:0xf
	v_cvt_pk_f16_f32 v28, v28, v29
	v_cvt_pk_f16_f32 v25, v24, v25
	v_cvt_pk_f16_f32 v24, v22, v23
	v_cndmask_b32_e64 v18, v19, v18, s[0:1]
	v_cndmask_b32_e64 v22, v26, v21, s[0:1]
	v_mov_b32_e32 v19, v1
	v_mov_b32_e32 v21, v1
	v_pk_mul_f32 v[30:31], v[30:31], v[2:3]
	v_mov_b32_dpp v19, v28 quad_perm:[1,0,3,2] row_mask:0xf bank_mask:0xf
	v_mov_b32_dpp v21, v20 quad_perm:[1,0,3,2] row_mask:0xf bank_mask:0xf
	v_cvt_pk_f16_f32 v30, v30, v31
	v_cndmask_b32_e64 v19, v19, v20, s[0:1]
	v_cndmask_b32_e64 v23, v28, v21, s[0:1]
	v_mov_b32_e32 v20, v1
	v_mov_b32_e32 v21, v1
	v_pk_mul_f32 v[32:33], v[32:33], v[4:5]
	v_mov_b32_dpp v20, v30 quad_perm:[1,0,3,2] row_mask:0xf bank_mask:0xf
	v_mov_b32_dpp v21, v24 quad_perm:[1,0,3,2] row_mask:0xf bank_mask:0xf
	v_cvt_pk_f16_f32 v32, v32, v33
	v_cndmask_b32_e64 v20, v20, v24, s[0:1]
	v_cndmask_b32_e64 v24, v30, v21, s[0:1]
	v_mov_b32_e32 v21, v1
	v_mov_b32_e32 v26, v1
	v_add_u32_e32 v27, 0x3dd8000, v0
	v_mov_b32_dpp v21, v32 quad_perm:[1,0,3,2] row_mask:0xf bank_mask:0xf
	v_mov_b32_dpp v26, v25 quad_perm:[1,0,3,2] row_mask:0xf bank_mask:0xf
	v_cndmask_b32_e64 v21, v21, v25, s[0:1]
	v_cndmask_b32_e64 v25, v32, v26, s[0:1]
	v_add_u32_e32 v0, 0x3dd8800, v0
	global_store_dwordx4 v27, v[18:21], s[38:39]
	global_store_dwordx4 v0, v[22:25], s[38:39]
